# NSA selected branch: both 32-key tiles of a 64-key selection block processed jointly (8 QK MFMAs into two score blocks, one max/rescale/row-sum pass over 64 scores, 8 PV MFMAs); K-DMA in attn_run swee
# speedup vs baseline: 1.1850x; 1.0093x over previous
.LBB0_490:
	s_ashr_i32 s0, s42, 2
	s_and_b32 s0, s0, -8
	v_readlane_b32 s12, v254, 38
	s_add_i32 s38, s0, s12
	s_mul_hi_i32 s0, s38, 0x2aaaaaab
	s_lshr_b32 s1, s0, 31
	s_add_i32 s0, s0, s1
	s_mul_i32 s1, s0, 6
	s_sub_i32 s43, s38, s1
	s_lshl_b32 s1, s42, 7
	s_and_b32 s40, s1, 0xe00
	s_lshl_b32 s1, s42, 2
	v_mov_b32_e32 v0, v199
	s_and_b32 s1, s1, 12
	v_add_u32_e32 v162, s1, v161
	v_and_b32_e32 v175, 31, v0
	v_and_b32_e32 v174, 63, v0
	v_bfe_u32 v10, v0, 5, 1
	v_lshl_or_b32 v0, v175, 4, s40
	v_add_u32_e32 v2, v0, v162
	s_ashr_i32 s1, s0, 31
	s_lshl_b64 s[36:37], s[0:1], 12
	v_ashrrev_i32_e32 v3, 31, v2
	v_lshl_add_u64 v[158:159], s[36:37], 0, v[2:3]
	v_mov_b64_e32 v[2:3], s[66:67]
	v_mad_u64_u32 v[2:3], s[0:1], v158, s80, v[2:3]
	s_lshl_b32 s0, s43, 6
	v_mad_i32_i24 v3, v159, s80, v3
	s_ashr_i32 s1, s0, 31
	v_lshl_add_u64 v[4:5], s[0:1], 1, v[2:3]
	v_lshlrev_b32_e32 v0, 4, v10
	v_lshlrev_b32_e32 v160, 3, v10
	v_lshl_add_u64 v[4:5], v[4:5], 0, v[0:1]
	s_add_i32 s30, s0, 0x180
	s_ashr_i32 s39, s38, 31
	v_readlane_b32 s44, v253, 2
	global_load_dwordx4 v[82:85], v[4:5], off
	global_load_dwordx4 v[86:89], v[4:5], off offset:32
	global_load_dwordx4 v[90:93], v[4:5], off offset:64
	global_load_dwordx4 v[94:97], v[4:5], off offset:96
	v_or_b32_e32 v4, s30, v160
	s_lshl_b64 s[38:39], s[38:39], 19
	s_lshl_b32 s30, s40, 3
	v_readlane_b32 s48, v253, 6
	v_ashrrev_i32_e32 v163, 31, v162
	v_readlane_b32 s49, v253, 7
	s_add_u32 s38, s48, s38
	v_lshlrev_b64 v[6:7], 15, v[162:163]
	s_addc_u32 s39, s49, s39
	v_mov_b32_e32 v5, v1
	v_lshl_add_u64 v[6:7], s[38:39], 0, v[6:7]
	v_lshlrev_b64 v[4:5], 1, v[4:5]
	v_lshl_add_u64 v[8:9], v[6:7], 0, s[30:31]
	v_lshlrev_b32_e32 v0, 5, v174
	v_lshl_add_u64 v[2:3], v[2:3], 0, v[4:5]
	v_lshl_add_u64 v[8:9], v[8:9], 0, v[0:1]
	v_and_b32_e32 v238, 63, v199
	v_lshrrev_b32_e32 v239, 3, v238
	v_and_b32_e32 v240, 31, v238
	v_lshrrev_b32_e32 v241, 5, v238
	v_and_b32_e32 v242, 7, v238
	v_lshrrev_b32_e32 v243, 4, v238
	v_xor_b32_e32 v228, v242, v243
	v_xor_b32_e32 v229, 4, v228
	v_lshlrev_b32_e32 v228, 4, v228
	v_lshlrev_b32_e32 v229, 4, v229
	v_mov_b32_e32 v224, 0x1c000
	v_mul_lo_u32 v225, v239, v224
	v_add_u32_e32 v244, v225, v228
	v_add_u32_e32 v245, 0xe0000, v225
	v_add_u32_e32 v245, v245, v229
	v_add_u32_e32 v246, 0x1c0000, v225
	v_add_u32_e32 v246, v246, v228
	v_add_u32_e32 v247, 0x2a0000, v225
	v_add_u32_e32 v247, v247, v229
	v_lshrrev_b32_e32 v250, 6, v199
	v_lshlrev_b32_e32 v250, 13, v250
	v_bfe_u32 v251, v238, 1, 3
	v_xor_b32_e32 v251, v251, v241
	v_lshlrev_b32_e32 v251, 4, v251
	v_lshl_add_u32 v251, v240, 7, v251
	v_add_u32_e32 v234, v250, v251
	v_xor_b32_e32 v235, 0x20, v234
	v_xor_b32_e32 v236, 0x40, v234
	v_xor_b32_e32 v237, 0x60, v234
	v_readfirstlane_b32 s98, v250
	v_readfirstlane_b32 s100, v2
	v_readfirstlane_b32 s101, v3
	s_add_u32 m0, s98, 0x0
	s_nop 4
	global_load_lds_dwordx4 v244, s[100:101]
	s_add_u32 m0, s98, 0x400
	s_nop 0
	global_load_lds_dwordx4 v245, s[100:101]
	s_add_u32 m0, s98, 0x800
	s_nop 0
	global_load_lds_dwordx4 v246, s[100:101]
	s_add_u32 m0, s98, 0xc00
	s_nop 0
	global_load_lds_dwordx4 v247, s[100:101]
	v_and_b32_e32 v230, 63, v199
	v_lshlrev_b32_e32 v230, 4, v230
	v_sub_u32_e32 v230, 0, v230
	v_ashrrev_i32_e32 v231, 31, v230
	v_lshl_add_u64 v[230:231], v[8:9], 0, v[230:231]
	global_load_dwordx4 v[110:113], v[230:231], off
	global_load_dwordx4 v[106:109], v[230:231], off offset:1024
	global_load_dwordx4 v[102:105], v[230:231], off offset:2048
	global_load_dwordx4 v[98:101], v[230:231], off offset:3072
	v_lshl_or_b32 v163, v10, 2, v213
	v_lshl_add_u64 v[164:165], v[6:7], 0, v[0:1]
	v_lshl_add_u64 v[166:167], s[66:67], 0, v[4:5]
	v_mov_b32_e32 v2, v1
	v_mov_b32_e32 v3, v1
	v_mov_b32_e32 v4, v1
	v_mov_b32_e32 v5, v1
	v_mov_b32_e32 v6, v1
	v_mov_b32_e32 v7, v1
	v_mov_b32_e32 v8, v1
	v_mov_b32_e32 v9, v1
	v_mov_b32_e32 v10, v1
	v_mov_b32_e32 v11, v1
	v_mov_b32_e32 v12, v1
	v_mov_b32_e32 v13, v1
	v_mov_b32_e32 v14, v1
	v_mov_b32_e32 v15, v1
	v_mov_b32_e32 v16, v1
	v_mov_b32_e32 v17, v1
	v_mov_b32_e32 v18, v1
	v_mov_b32_e32 v19, v1
	v_mov_b32_e32 v20, v1
	v_mov_b32_e32 v21, v1
	v_mov_b32_e32 v22, v1
	v_mov_b32_e32 v23, v1
	v_mov_b32_e32 v24, v1
	v_mov_b32_e32 v25, v1
	v_mov_b32_e32 v26, v1
	v_mov_b32_e32 v27, v1
	v_mov_b32_e32 v28, v1
	v_mov_b32_e32 v29, v1
	v_mov_b32_e32 v30, v1
	v_mov_b32_e32 v31, v1
	v_mov_b32_e32 v0, v1
	v_mov_b64_e32 v[32:33], v[30:31]
	s_lshr_b32 s30, s40, 4
	s_mov_b32 s44, 0
	v_mov_b32_e32 v173, 0xc61c4000
	v_mov_b32_e32 v171, 0
	v_mov_b64_e32 v[30:31], v[28:29]
	v_mov_b64_e32 v[28:29], v[26:27]
	v_mov_b64_e32 v[26:27], v[24:25]
	v_mov_b64_e32 v[24:25], v[22:23]
	v_mov_b64_e32 v[22:23], v[20:21]
	v_mov_b64_e32 v[20:21], v[18:19]
	v_mov_b64_e32 v[18:19], v[16:17]
	v_mov_b64_e32 v[16:17], v[14:15]
	v_mov_b64_e32 v[14:15], v[12:13]
	v_mov_b64_e32 v[12:13], v[10:11]
	v_mov_b64_e32 v[10:11], v[8:9]
	v_mov_b64_e32 v[8:9], v[6:7]
	v_mov_b64_e32 v[6:7], v[4:5]
	v_mov_b64_e32 v[4:5], v[2:3]
	v_mov_b64_e32 v[2:3], v[0:1]
	v_readlane_b32 s13, v254, 39
	v_readlane_b32 s45, v253, 3
	v_readlane_b32 s46, v253, 4
	v_readlane_b32 s47, v253, 5
	v_readlane_b32 s50, v253, 8
	v_readlane_b32 s51, v253, 9
	v_readlane_b32 s52, v253, 10
	v_readlane_b32 s53, v253, 11
	v_readlane_b32 s54, v253, 12
	v_readlane_b32 s55, v253, 13
	v_readlane_b32 s56, v253, 14
	v_readlane_b32 s57, v253, 15
	v_readlane_b32 s58, v253, 16
	v_readlane_b32 s59, v253, 17
	s_branch .LBB0_494

.LBB0_498:
	s_cmp_gt_i32 s45, -1
	s_cselect_b64 s[38:39], -1, 0
	s_cmp_lt_i32 s45, 0
	s_cselect_b32 s41, s44, s45
	s_lshl_b32 s41, s41, 5
	s_sub_i32 s41, s30, s41
	v_or_b32_e32 v0, s41, v175
	v_lshl_add_u32 v50, v0, 4, v162
	s_ashr_i32 s46, s41, 5
	s_ashr_i32 s47, s46, 31
	v_ashrrev_i32_e32 v51, 31, v50
	s_lshl_b64 s[46:47], s[46:47], 12
	v_lshl_add_u64 v[50:51], s[36:37], 0, v[50:51]
	v_lshl_add_u64 v[52:53], v[164:165], 0, s[46:47]
	v_mad_u64_u32 v[54:55], s[46:47], v50, s80, v[166:167]
	v_mad_i32_i24 v55, v51, s80, v55
	v_readfirstlane_b32 s100, v54
	v_readfirstlane_b32 s101, v55
	s_add_u32 m0, s98, 0x1000
	s_nop 4
	global_load_lds_dwordx4 v244, s[100:101]
	s_add_u32 m0, s98, 0x1400
	s_nop 0
	global_load_lds_dwordx4 v245, s[100:101]
	s_add_u32 m0, s98, 0x1800
	s_nop 0
	global_load_lds_dwordx4 v246, s[100:101]
	s_add_u32 m0, s98, 0x1c00
	s_nop 0
	global_load_lds_dwordx4 v247, s[100:101]
	v_and_b32_e32 v230, 63, v199
	v_lshlrev_b32_e32 v230, 4, v230
	v_sub_u32_e32 v230, 0, v230
	v_ashrrev_i32_e32 v231, 31, v230
	v_lshl_add_u64 v[230:231], v[52:53], 0, v[230:231]
	global_load_dwordx4 v[126:129], v[230:231], off
	global_load_dwordx4 v[122:125], v[230:231], off offset:1024
	global_load_dwordx4 v[118:121], v[230:231], off offset:2048
	global_load_dwordx4 v[114:117], v[230:231], off offset:3072
	s_waitcnt vmcnt(12)
	ds_read_b128 v[142:145], v234
	ds_read_b128 v[134:137], v235
	ds_read_b128 v[130:133], v236
	ds_read_b128 v[138:141], v237
	s_waitcnt lgkmcnt(3)
	v_mfma_f32_32x32x16_bf16 v[34:49], v[142:145], v[82:85], 0
	v_or_b32_e32 v0, s40, v175
	v_add_u32_e32 v50, 0xffffff7f, v0
	v_cmp_gt_u32_e32 vcc, s2, v50
	s_waitcnt lgkmcnt(2)
	v_mfma_f32_32x32x16_bf16 v[34:49], v[134:137], v[86:89], v[34:49]
	s_waitcnt lgkmcnt(1)
	v_mfma_f32_32x32x16_bf16 v[34:49], v[130:133], v[90:93], v[34:49]
	s_waitcnt lgkmcnt(0)
	v_mfma_f32_32x32x16_bf16 v[34:49], v[138:141], v[94:97], v[34:49]
	s_cbranch_vccz .LBB0_500
	v_sub_u32_e32 v0, v163, v0
	v_cmp_gt_u32_e32 vcc, s3, v0
	v_add_u32_e32 v50, 0xffffff80, v0
	s_nop 7
	v_cndmask_b32_e32 v34, v212, v34, vcc
	v_cmp_lt_u32_e32 vcc, s8, v50
	v_add_u32_e32 v50, 0xffffff81, v0
	s_nop 0
	v_cndmask_b32_e32 v35, v212, v35, vcc
	v_cmp_lt_u32_e32 vcc, s8, v50
	v_add_u32_e32 v50, 0xffffff82, v0
	s_nop 0
	v_cndmask_b32_e32 v36, v212, v36, vcc
	v_cmp_lt_u32_e32 vcc, s8, v50
	v_add_u32_e32 v50, 0xffffff87, v0
	s_nop 0
	v_cndmask_b32_e32 v37, v212, v37, vcc
	v_cmp_lt_u32_e32 vcc, s8, v50
	v_add_u32_e32 v50, 0xffffff88, v0
	s_nop 0
	v_cndmask_b32_e32 v38, v212, v38, vcc
	v_cmp_lt_u32_e32 vcc, s8, v50
	v_add_u32_e32 v50, 0xffffff89, v0
	s_nop 0
	v_cndmask_b32_e32 v39, v212, v39, vcc
	v_cmp_lt_u32_e32 vcc, s8, v50
	v_add_u32_e32 v50, 0xffffff8a, v0
	s_nop 0
	v_cndmask_b32_e32 v40, v212, v40, vcc
	v_cmp_lt_u32_e32 vcc, s8, v50
	v_add_u32_e32 v50, 0xffffff8f, v0
	s_nop 0
	v_cndmask_b32_e32 v41, v212, v41, vcc
	v_cmp_lt_u32_e32 vcc, s8, v50
	v_add_u32_e32 v50, 0xffffff90, v0
	s_nop 0
	v_cndmask_b32_e32 v42, v212, v42, vcc
	v_cmp_lt_u32_e32 vcc, s8, v50
	v_add_u32_e32 v50, 0xffffff91, v0
	s_nop 0
	v_cndmask_b32_e32 v43, v212, v43, vcc
	v_cmp_lt_u32_e32 vcc, s8, v50
	v_add_u32_e32 v50, 0xffffff92, v0
	s_nop 0
	v_cndmask_b32_e32 v44, v212, v44, vcc
	v_cmp_lt_u32_e32 vcc, s8, v50
	v_add_u32_e32 v50, 0xffffff97, v0
	s_nop 0
	v_cndmask_b32_e32 v45, v212, v45, vcc
	v_cmp_lt_u32_e32 vcc, s8, v50
	v_add_u32_e32 v50, 0xffffff98, v0
	s_nop 0
	v_cndmask_b32_e32 v46, v212, v46, vcc
	v_cmp_lt_u32_e32 vcc, s8, v50
	v_add_u32_e32 v50, 0xffffff99, v0
	v_add_u32_e32 v0, 0xffffff9a, v0
	v_cndmask_b32_e32 v47, v212, v47, vcc
	v_cmp_lt_u32_e32 vcc, s8, v50
	s_nop 1
	v_cndmask_b32_e32 v48, v212, v48, vcc
	v_cmp_lt_u32_e32 vcc, s8, v0
	s_nop 1
	v_cndmask_b32_e32 v49, v212, v49, vcc

.LBB0_508:
	s_cmp_lt_i32 s44, 0
	s_cselect_b64 s[38:39], -1, 0
	s_cmp_gt_i32 s44, -1
	s_cselect_b32 s41, s44, s45
	s_lshl_b32 s41, s41, 5
	s_sub_i32 s41, s30, s41
	v_or_b32_e32 v0, s41, v175
	v_lshl_add_u32 v2, v0, 4, v162
	s_ashr_i32 s46, s41, 5
	s_ashr_i32 s47, s46, 31
	v_ashrrev_i32_e32 v3, 31, v2
	s_lshl_b64 s[46:47], s[46:47], 12
	v_lshl_add_u64 v[2:3], s[36:37], 0, v[2:3]
	v_lshl_add_u64 v[4:5], v[164:165], 0, s[46:47]
	v_mad_u64_u32 v[6:7], s[46:47], v2, s80, v[166:167]
	v_mad_i32_i24 v7, v3, s80, v7
	v_readfirstlane_b32 s100, v6
	v_readfirstlane_b32 s101, v7
	s_add_u32 m0, s98, 0x0
	s_nop 4
	global_load_lds_dwordx4 v244, s[100:101]
	s_add_u32 m0, s98, 0x400
	s_nop 0
	global_load_lds_dwordx4 v245, s[100:101]
	s_add_u32 m0, s98, 0x800
	s_nop 0
	global_load_lds_dwordx4 v246, s[100:101]
	s_add_u32 m0, s98, 0xc00
	s_nop 0
	global_load_lds_dwordx4 v247, s[100:101]
	v_and_b32_e32 v230, 63, v199
	v_lshlrev_b32_e32 v230, 4, v230
	v_sub_u32_e32 v230, 0, v230
	v_ashrrev_i32_e32 v231, 31, v230
	v_lshl_add_u64 v[230:231], v[4:5], 0, v[230:231]
	global_load_dwordx4 v[110:113], v[230:231], off
	global_load_dwordx4 v[106:109], v[230:231], off offset:1024
	global_load_dwordx4 v[102:105], v[230:231], off offset:2048
	global_load_dwordx4 v[98:101], v[230:231], off offset:3072
	s_waitcnt vmcnt(12)
	ds_read_b128 v[66:69], v234 offset:4096
	ds_read_b128 v[154:157], v235 offset:4096
	ds_read_b128 v[150:153], v236 offset:4096
	ds_read_b128 v[146:149], v237 offset:4096
	s_waitcnt lgkmcnt(3)
	v_mfma_f32_32x32x16_bf16 v[66:81], v[66:69], v[82:85], 0
	v_or_b32_e32 v0, s40, v175
	v_add_u32_e32 v2, 0xffffff7f, v0
	v_cmp_gt_u32_e32 vcc, s2, v2
	s_waitcnt lgkmcnt(2)
	v_mfma_f32_32x32x16_bf16 v[66:81], v[154:157], v[86:89], v[66:81]
	s_waitcnt lgkmcnt(1)
	v_mfma_f32_32x32x16_bf16 v[66:81], v[150:153], v[90:93], v[66:81]
	s_waitcnt lgkmcnt(0)
	v_mfma_f32_32x32x16_bf16 v[66:81], v[146:149], v[94:97], v[66:81]
	s_cbranch_vccz .LBB0_510
	v_sub_u32_e32 v0, v163, v0
	v_cmp_gt_u32_e32 vcc, s3, v0
	v_add_u32_e32 v2, 0xffffff80, v0
	s_nop 7
	v_cndmask_b32_e32 v66, v212, v66, vcc
	v_cmp_lt_u32_e32 vcc, s8, v2
	v_add_u32_e32 v2, 0xffffff81, v0
	s_nop 0
	v_cndmask_b32_e32 v67, v212, v67, vcc
	v_cmp_lt_u32_e32 vcc, s8, v2
	v_add_u32_e32 v2, 0xffffff82, v0
	s_nop 0
	v_cndmask_b32_e32 v68, v212, v68, vcc
	v_cmp_lt_u32_e32 vcc, s8, v2
	v_add_u32_e32 v2, 0xffffff87, v0
	s_nop 0
	v_cndmask_b32_e32 v69, v212, v69, vcc
	v_cmp_lt_u32_e32 vcc, s8, v2
	v_add_u32_e32 v2, 0xffffff88, v0
	s_nop 0
	v_cndmask_b32_e32 v70, v212, v70, vcc
	v_cmp_lt_u32_e32 vcc, s8, v2
	v_add_u32_e32 v2, 0xffffff89, v0
	s_nop 0
	v_cndmask_b32_e32 v71, v212, v71, vcc
	v_cmp_lt_u32_e32 vcc, s8, v2
	v_add_u32_e32 v2, 0xffffff8a, v0
	s_nop 0
	v_cndmask_b32_e32 v72, v212, v72, vcc
	v_cmp_lt_u32_e32 vcc, s8, v2
	v_add_u32_e32 v2, 0xffffff8f, v0
	s_nop 0
	v_cndmask_b32_e32 v73, v212, v73, vcc
	v_cmp_lt_u32_e32 vcc, s8, v2
	v_add_u32_e32 v2, 0xffffff90, v0
	s_nop 0
	v_cndmask_b32_e32 v74, v212, v74, vcc
	v_cmp_lt_u32_e32 vcc, s8, v2
	v_add_u32_e32 v2, 0xffffff91, v0
	s_nop 0
	v_cndmask_b32_e32 v75, v212, v75, vcc
	v_cmp_lt_u32_e32 vcc, s8, v2
	v_add_u32_e32 v2, 0xffffff92, v0
	s_nop 0
	v_cndmask_b32_e32 v76, v212, v76, vcc
	v_cmp_lt_u32_e32 vcc, s8, v2
	v_add_u32_e32 v2, 0xffffff97, v0
	s_nop 0
	v_cndmask_b32_e32 v77, v212, v77, vcc
	v_cmp_lt_u32_e32 vcc, s8, v2
	v_add_u32_e32 v2, 0xffffff98, v0
	s_nop 0
	v_cndmask_b32_e32 v78, v212, v78, vcc
	v_cmp_lt_u32_e32 vcc, s8, v2
	v_add_u32_e32 v2, 0xffffff99, v0
	v_add_u32_e32 v0, 0xffffff9a, v0
	v_cndmask_b32_e32 v79, v212, v79, vcc
	v_cmp_lt_u32_e32 vcc, s8, v2
	s_nop 1
	v_cndmask_b32_e32 v80, v212, v80, vcc
	v_cmp_lt_u32_e32 vcc, s8, v0
	s_nop 1
	v_cndmask_b32_e32 v81, v212, v81, vcc

.LBB0_685:
	s_cmp_lg_u32 s40, 0
	s_cbranch_scc1 .Lnsj_old
	s_or_b32 s41, 1, s55
	s_cmp_gt_i32 s41, s44
	s_cbranch_scc1 .Lnsj_old
	v_add_u32_e32 v0, s53, v141
	v_add_u32_e32 v66, v0, v166
	ds_read_b128 v[66:69], v66 offset:34816
	v_add_u32_e32 v98, v0, v172
	ds_read_b128 v[98:101], v98 offset:34816
	v_add_u32_e32 v102, v0, v173
	ds_read_b128 v[102:105], v102 offset:34816
	v_add_u32_e32 v178, v0, v174
	ds_read_b128 v[178:181], v178 offset:34816
	v_add_u32_e32 v220, v0, v166
	ds_read_b128 v[220:223], v220 offset:43008
	v_add_u32_e32 v106, v0, v172
	ds_read_b128 v[106:109], v106 offset:43008
	v_add_u32_e32 v110, v0, v173
	ds_read_b128 v[110:113], v110 offset:43008
	v_add_u32_e32 v236, v0, v174
	ds_read_b128 v[236:239], v236 offset:43008
	v_subrev_u32_e32 v0, s30, v130
	v_cndmask_b32_e64 v0, v0, v217, s[38:39]
	s_waitcnt lgkmcnt(7)
	v_mfma_f32_32x32x16_bf16 v[66:81], v[66:69], v[114:117], 0
	s_waitcnt lgkmcnt(6)
	v_mfma_f32_32x32x16_bf16 v[66:81], v[98:101], v[118:121], v[66:81]
	s_waitcnt lgkmcnt(5)
	v_mfma_f32_32x32x16_bf16 v[66:81], v[102:105], v[122:125], v[66:81]
	s_waitcnt lgkmcnt(4)
	v_mfma_f32_32x32x16_bf16 v[66:81], v[178:181], v[126:129], v[66:81]
	s_waitcnt lgkmcnt(3)
	v_mfma_f32_32x32x16_bf16 v[220:235], v[220:223], v[114:117], 0
	s_waitcnt lgkmcnt(2)
	v_mfma_f32_32x32x16_bf16 v[220:235], v[106:109], v[118:121], v[220:235]
	s_waitcnt lgkmcnt(1)
	v_mfma_f32_32x32x16_bf16 v[220:235], v[110:113], v[122:125], v[220:235]
	s_waitcnt lgkmcnt(0)
	v_mfma_f32_32x32x16_bf16 v[220:235], v[236:239], v[126:129], v[220:235]
	v_add_u32_e32 v177, s53, v175
	ds_read_b128 v[110:113], v177 offset:38912
	ds_read_b128 v[106:109], v177 offset:39936
	ds_read_b128 v[102:105], v177 offset:40960
	ds_read_b128 v[98:101], v177 offset:41984
	ds_read_b128 v[236:239], v177 offset:47104
	ds_read_b128 v[240:243], v177 offset:48128
	ds_read_b128 v[244:247], v177 offset:49152
	ds_read_b128 v[248:251], v177 offset:50176
	v_add_u32_e32 v177, 0x186a0, v0
	v_subrev_u32_e32 v178, 32, v177
	v_cmp_lt_i32_e64 s[40:41], s96, v0
	s_nop 7
	s_nop 7
	v_cmp_gt_u32_e32 vcc, s9, v177
	s_cbranch_vccz .Lnsj_nomask_a
	v_cmp_le_u32_e32 vcc, v142, v177
	s_nop 1
	v_cndmask_b32_e32 v66, v212, v66, vcc
	v_cmp_le_u32_e32 vcc, v143, v177
	s_nop 1
	v_cndmask_b32_e32 v67, v212, v67, vcc
	v_cmp_le_u32_e32 vcc, v144, v177
	s_nop 1
	v_cndmask_b32_e32 v68, v212, v68, vcc
	v_cmp_le_u32_e32 vcc, v145, v177
	s_nop 1
	v_cndmask_b32_e32 v69, v212, v69, vcc
	v_cmp_le_u32_e32 vcc, v146, v177
	s_nop 1
	v_cndmask_b32_e32 v70, v212, v70, vcc
	v_cmp_le_u32_e32 vcc, v147, v177
	s_nop 1
	v_cndmask_b32_e32 v71, v212, v71, vcc
	v_cmp_le_u32_e32 vcc, v148, v177
	s_nop 1
	v_cndmask_b32_e32 v72, v212, v72, vcc
	v_cmp_le_u32_e32 vcc, v149, v177
	s_nop 1
	v_cndmask_b32_e32 v73, v212, v73, vcc
	v_cmp_le_u32_e32 vcc, v150, v177
	s_nop 1
	v_cndmask_b32_e32 v74, v212, v74, vcc
	v_cmp_le_u32_e32 vcc, v151, v177
	s_nop 1
	v_cndmask_b32_e32 v75, v212, v75, vcc
	v_cmp_le_u32_e32 vcc, v152, v177
	s_nop 1
	v_cndmask_b32_e32 v76, v212, v76, vcc
	v_cmp_le_u32_e32 vcc, v153, v177
	s_nop 1
	v_cndmask_b32_e32 v77, v212, v77, vcc
	v_cmp_le_u32_e32 vcc, v162, v177
	s_nop 1
	v_cndmask_b32_e32 v78, v212, v78, vcc
	v_cmp_le_u32_e32 vcc, v163, v177
	s_nop 1
	v_cndmask_b32_e32 v79, v212, v79, vcc
	v_cmp_le_u32_e32 vcc, v164, v177
	s_nop 1
	v_cndmask_b32_e32 v80, v212, v80, vcc
	v_cmp_le_u32_e32 vcc, v165, v177
	s_nop 1
	v_cndmask_b32_e32 v81, v212, v81, vcc
.Lnsj_nomask_a:
	v_cmp_gt_u32_e32 vcc, s9, v178
	s_cbranch_vccz .Lnsj_nomask_b
	v_cmp_le_u32_e32 vcc, v142, v178
	s_nop 1
	v_cndmask_b32_e32 v220, v212, v220, vcc
	v_cmp_le_u32_e32 vcc, v143, v178
	s_nop 1
	v_cndmask_b32_e32 v221, v212, v221, vcc
	v_cmp_le_u32_e32 vcc, v144, v178
	s_nop 1
	v_cndmask_b32_e32 v222, v212, v222, vcc
	v_cmp_le_u32_e32 vcc, v145, v178
	s_nop 1
	v_cndmask_b32_e32 v223, v212, v223, vcc
	v_cmp_le_u32_e32 vcc, v146, v178
	s_nop 1
	v_cndmask_b32_e32 v224, v212, v224, vcc
	v_cmp_le_u32_e32 vcc, v147, v178
	s_nop 1
	v_cndmask_b32_e32 v225, v212, v225, vcc
	v_cmp_le_u32_e32 vcc, v148, v178
	s_nop 1
	v_cndmask_b32_e32 v226, v212, v226, vcc
	v_cmp_le_u32_e32 vcc, v149, v178
	s_nop 1
	v_cndmask_b32_e32 v227, v212, v227, vcc
	v_cmp_le_u32_e32 vcc, v150, v178
	s_nop 1
	v_cndmask_b32_e32 v228, v212, v228, vcc
	v_cmp_le_u32_e32 vcc, v151, v178
	s_nop 1
	v_cndmask_b32_e32 v229, v212, v229, vcc
	v_cmp_le_u32_e32 vcc, v152, v178
	s_nop 1
	v_cndmask_b32_e32 v230, v212, v230, vcc
	v_cmp_le_u32_e32 vcc, v153, v178
	s_nop 1
	v_cndmask_b32_e32 v231, v212, v231, vcc
	v_cmp_le_u32_e32 vcc, v162, v178
	s_nop 1
	v_cndmask_b32_e32 v232, v212, v232, vcc
	v_cmp_le_u32_e32 vcc, v163, v178
	s_nop 1
	v_cndmask_b32_e32 v233, v212, v233, vcc
	v_cmp_le_u32_e32 vcc, v164, v178
	s_nop 1
	v_cndmask_b32_e32 v234, v212, v234, vcc
	v_cmp_le_u32_e32 vcc, v165, v178
	s_nop 1
	v_cndmask_b32_e32 v235, v212, v235, vcc
.Lnsj_nomask_b:
	v_max3_f32 v0, v66, v67, v68
	v_max3_f32 v179, v69, v70, v71
	v_max3_f32 v180, v72, v73, v74
	v_max3_f32 v0, v0, v179, v180
	v_max3_f32 v179, v75, v76, v77
	v_max3_f32 v180, v78, v79, v80
	v_max3_f32 v181, v220, v221, v222
	v_max3_f32 v179, v179, v180, v181
	v_max3_f32 v180, v223, v224, v225
	v_max3_f32 v181, v226, v227, v228
	v_max3_f32 v177, v229, v230, v231
	v_max3_f32 v180, v180, v181, v177
	v_max3_f32 v181, v232, v233, v234
	v_max3_f32 v181, v181, v81, v235
	v_max3_f32 v0, v0, v179, v180
	v_max_f32_e32 v0, v0, v181
	v_cndmask_b32_e64 v0, v212, v0, s[40:41]
	v_mov_b32_e32 v177, v0
	s_nop 1
	v_permlane32_swap_b32_e32 v0, v177
	v_max_f32_e32 v0, v0, v177
	v_add_f32_e32 v177, 0x41800000, v176
	v_cmp_gt_f32_e32 vcc, v0, v177
	s_cbranch_vccz .Lnsj_norescale
	s_nop 0
	v_cndmask_b32_e32 v177, v176, v0, vcc
	v_sub_f32_e32 v0, v176, v177
	v_exp_f32_e32 v0, v0
	v_mov_b32_e32 v176, v177
	s_nop 0
	v_mul_f32_e32 v161, v161, v0
	v_pk_mul_f32 v[64:65], v[64:65], v[0:1] op_sel_hi:[1,0]
	v_pk_mul_f32 v[62:63], v[62:63], v[0:1] op_sel_hi:[1,0]
	v_pk_mul_f32 v[60:61], v[60:61], v[0:1] op_sel_hi:[1,0]
	v_pk_mul_f32 v[58:59], v[58:59], v[0:1] op_sel_hi:[1,0]
	v_pk_mul_f32 v[56:57], v[56:57], v[0:1] op_sel_hi:[1,0]
	v_pk_mul_f32 v[54:55], v[54:55], v[0:1] op_sel_hi:[1,0]
	v_pk_mul_f32 v[52:53], v[52:53], v[0:1] op_sel_hi:[1,0]
	v_pk_mul_f32 v[50:51], v[50:51], v[0:1] op_sel_hi:[1,0]
	v_pk_mul_f32 v[48:49], v[48:49], v[0:1] op_sel_hi:[1,0]
	v_pk_mul_f32 v[46:47], v[46:47], v[0:1] op_sel_hi:[1,0]
	v_pk_mul_f32 v[44:45], v[44:45], v[0:1] op_sel_hi:[1,0]
	v_pk_mul_f32 v[42:43], v[42:43], v[0:1] op_sel_hi:[1,0]
	v_pk_mul_f32 v[40:41], v[40:41], v[0:1] op_sel_hi:[1,0]
	v_pk_mul_f32 v[38:39], v[38:39], v[0:1] op_sel_hi:[1,0]
	v_pk_mul_f32 v[36:37], v[36:37], v[0:1] op_sel_hi:[1,0]
	v_pk_mul_f32 v[34:35], v[34:35], v[0:1] op_sel_hi:[1,0]
.Lnsj_norescale:
	v_cndmask_b32_e64 v0, v214, v176, s[40:41]
	v_pk_add_f32 v[66:67], v[66:67], v[0:1] op_sel_hi:[1,0] neg_lo:[0,1] neg_hi:[0,1]
	v_pk_add_f32 v[68:69], v[68:69], v[0:1] op_sel_hi:[1,0] neg_lo:[0,1] neg_hi:[0,1]
	v_pk_add_f32 v[70:71], v[70:71], v[0:1] op_sel_hi:[1,0] neg_lo:[0,1] neg_hi:[0,1]
	v_pk_add_f32 v[72:73], v[72:73], v[0:1] op_sel_hi:[1,0] neg_lo:[0,1] neg_hi:[0,1]
	v_pk_add_f32 v[74:75], v[74:75], v[0:1] op_sel_hi:[1,0] neg_lo:[0,1] neg_hi:[0,1]
	v_pk_add_f32 v[76:77], v[76:77], v[0:1] op_sel_hi:[1,0] neg_lo:[0,1] neg_hi:[0,1]
	v_pk_add_f32 v[78:79], v[78:79], v[0:1] op_sel_hi:[1,0] neg_lo:[0,1] neg_hi:[0,1]
	v_pk_add_f32 v[80:81], v[80:81], v[0:1] op_sel_hi:[1,0] neg_lo:[0,1] neg_hi:[0,1]
	v_pk_add_f32 v[220:221], v[220:221], v[0:1] op_sel_hi:[1,0] neg_lo:[0,1] neg_hi:[0,1]
	v_pk_add_f32 v[222:223], v[222:223], v[0:1] op_sel_hi:[1,0] neg_lo:[0,1] neg_hi:[0,1]
	v_pk_add_f32 v[224:225], v[224:225], v[0:1] op_sel_hi:[1,0] neg_lo:[0,1] neg_hi:[0,1]
	v_pk_add_f32 v[226:227], v[226:227], v[0:1] op_sel_hi:[1,0] neg_lo:[0,1] neg_hi:[0,1]
	v_pk_add_f32 v[228:229], v[228:229], v[0:1] op_sel_hi:[1,0] neg_lo:[0,1] neg_hi:[0,1]
	v_pk_add_f32 v[230:231], v[230:231], v[0:1] op_sel_hi:[1,0] neg_lo:[0,1] neg_hi:[0,1]
	v_pk_add_f32 v[232:233], v[232:233], v[0:1] op_sel_hi:[1,0] neg_lo:[0,1] neg_hi:[0,1]
	v_pk_add_f32 v[234:235], v[234:235], v[0:1] op_sel_hi:[1,0] neg_lo:[0,1] neg_hi:[0,1]
	v_exp_f32_e32 v66, v66
	v_exp_f32_e32 v67, v67
	v_exp_f32_e32 v68, v68
	v_exp_f32_e32 v69, v69
	v_exp_f32_e32 v70, v70
	v_exp_f32_e32 v71, v71
	v_exp_f32_e32 v72, v72
	v_exp_f32_e32 v73, v73
	v_exp_f32_e32 v74, v74
	v_exp_f32_e32 v75, v75
	v_exp_f32_e32 v76, v76
	v_exp_f32_e32 v77, v77
	v_exp_f32_e32 v78, v78
	v_exp_f32_e32 v79, v79
	v_exp_f32_e32 v80, v80
	v_exp_f32_e32 v81, v81
	v_exp_f32_e32 v220, v220
	v_exp_f32_e32 v221, v221
	v_exp_f32_e32 v222, v222
	v_exp_f32_e32 v223, v223
	v_exp_f32_e32 v224, v224
	v_exp_f32_e32 v225, v225
	v_exp_f32_e32 v226, v226
	v_exp_f32_e32 v227, v227
	v_exp_f32_e32 v228, v228
	v_exp_f32_e32 v229, v229
	v_exp_f32_e32 v230, v230
	v_exp_f32_e32 v231, v231
	v_exp_f32_e32 v232, v232
	v_exp_f32_e32 v233, v233
	v_exp_f32_e32 v234, v234
	v_exp_f32_e32 v235, v235
	s_nop 0
	v_pk_add_f32 v[178:179], v[66:67], v[68:69]
	v_pk_add_f32 v[180:181], v[220:221], v[222:223]
	v_pk_add_f32 v[178:179], v[178:179], v[70:71]
	v_pk_add_f32 v[180:181], v[180:181], v[224:225]
	v_pk_add_f32 v[178:179], v[178:179], v[72:73]
	v_pk_add_f32 v[180:181], v[180:181], v[226:227]
	v_pk_add_f32 v[178:179], v[178:179], v[74:75]
	v_pk_add_f32 v[180:181], v[180:181], v[228:229]
	v_pk_add_f32 v[178:179], v[178:179], v[76:77]
	v_pk_add_f32 v[180:181], v[180:181], v[230:231]
	v_pk_add_f32 v[178:179], v[178:179], v[78:79]
	v_pk_add_f32 v[180:181], v[180:181], v[232:233]
	v_pk_add_f32 v[178:179], v[178:179], v[80:81]
	v_pk_add_f32 v[180:181], v[180:181], v[234:235]
	v_pk_add_f32 v[178:179], v[178:179], v[180:181]
	v_add_f32_e32 v0, v178, v179
	v_cvt_pk_bf16_f32 v66, v66, v67
	v_cvt_pk_bf16_f32 v67, v68, v69
	v_cvt_pk_bf16_f32 v68, v70, v71
	v_cvt_pk_bf16_f32 v69, v72, v73
	v_cvt_pk_bf16_f32 v70, v74, v75
	v_cvt_pk_bf16_f32 v71, v76, v77
	v_cvt_pk_bf16_f32 v72, v78, v79
	v_cvt_pk_bf16_f32 v73, v80, v81
	v_cvt_pk_bf16_f32 v220, v220, v221
	v_cvt_pk_bf16_f32 v221, v222, v223
	v_cvt_pk_bf16_f32 v222, v224, v225
	v_cvt_pk_bf16_f32 v223, v226, v227
	v_cvt_pk_bf16_f32 v224, v228, v229
	v_cvt_pk_bf16_f32 v225, v230, v231
	v_cvt_pk_bf16_f32 v226, v232, v233
	v_cvt_pk_bf16_f32 v227, v234, v235
	v_mov_b32_e32 v177, v0
	s_nop 1
	v_permlane32_swap_b32_e32 v0, v177
	v_add_f32_e32 v0, v0, v177
	v_add_f32_e32 v161, v161, v0
	s_waitcnt lgkmcnt(0)
	v_mfma_f32_32x32x16_bf16 v[34:49], v[110:113], v[66:69], v[34:49]
	v_mfma_f32_32x32x16_bf16 v[50:65], v[102:105], v[66:69], v[50:65]
	v_mfma_f32_32x32x16_bf16 v[34:49], v[106:109], v[70:73], v[34:49]
	v_mfma_f32_32x32x16_bf16 v[50:65], v[98:101], v[70:73], v[50:65]
	v_mfma_f32_32x32x16_bf16 v[34:49], v[236:239], v[220:223], v[34:49]
	v_mfma_f32_32x32x16_bf16 v[50:65], v[244:247], v[220:223], v[50:65]
	v_mfma_f32_32x32x16_bf16 v[34:49], v[240:243], v[224:227], v[34:49]
	v_mfma_f32_32x32x16_bf16 v[50:65], v[248:251], v[224:227], v[50:65]
	s_branch .LBB0_691

.LBB0_705:
	s_add_i32 s39, s40, 0x180
	s_lshr_b32 s43, s42, 2
	s_lshl_b32 s40, s44, 5
	s_add_i32 s40, s43, s40
	s_add_i32 s45, s40, 0xffffff80
	v_lshlrev_b32_e32 v36, 3, v34
	v_lshlrev_b32_e32 v30, 16, v0
	v_and_b32_e32 v31, 0xffff0000, v0
	v_or_b32_e32 v0, s45, v159
	v_or_b32_e32 v36, s39, v36
	s_ashr_i32 s39, s38, 31
	s_ashr_i32 s40, s45, 5
	v_lshl_add_u32 v38, v0, 2, v158
	s_ashr_i32 s41, s40, 31
	s_lshl_b64 s[38:39], s[38:39], 19
	v_ashrrev_i32_e32 v39, 31, v38
	s_lshl_b64 s[40:41], s[40:41], 12
	v_lshl_add_u64 v[170:171], v[160:161], 0, s[38:39]
	v_lshl_add_u64 v[38:39], s[0:1], 0, v[38:39]
	v_mov_b64_e32 v[42:43], s[66:67]
	v_lshl_add_u64 v[40:41], v[170:171], 0, s[40:41]
	v_mad_u64_u32 v[42:43], s[40:41], v38, s80, v[42:43]
	v_mov_b32_e32 v37, v1
	v_and_b32_e32 v35, 63, v2
	v_mad_i32_i24 v43, v39, s80, v43
	v_lshlrev_b64 v[36:37], 1, v[36:37]
	v_lshlrev_b32_e32 v0, 5, v35
	v_lshl_add_u64 v[38:39], v[42:43], 0, v[36:37]
	v_lshl_add_u64 v[40:41], v[40:41], 0, v[0:1]
	v_and_b32_e32 v238, 63, v199
	v_lshrrev_b32_e32 v239, 3, v238
	v_and_b32_e32 v240, 31, v238
	v_lshrrev_b32_e32 v241, 5, v238
	v_and_b32_e32 v242, 7, v238
	v_lshrrev_b32_e32 v243, 4, v238
	v_xor_b32_e32 v228, v242, v243
	v_xor_b32_e32 v229, 4, v228
	v_lshlrev_b32_e32 v228, 4, v228
	v_lshlrev_b32_e32 v229, 4, v229
	v_mov_b32_e32 v224, 0x7000
	v_mul_lo_u32 v225, v239, v224
	v_add_u32_e32 v244, v225, v228
	v_add_u32_e32 v245, 0x38000, v225
	v_add_u32_e32 v245, v245, v229
	v_add_u32_e32 v246, 0x70000, v225
	v_add_u32_e32 v246, v246, v228
	v_add_u32_e32 v247, 0xa8000, v225
	v_add_u32_e32 v247, v247, v229
	v_lshrrev_b32_e32 v250, 6, v199
	v_lshlrev_b32_e32 v250, 13, v250
	v_bfe_u32 v251, v238, 1, 3
	v_xor_b32_e32 v251, v251, v241
	v_lshlrev_b32_e32 v251, 4, v251
	v_lshl_add_u32 v251, v240, 7, v251
	v_add_u32_e32 v234, v250, v251
	v_xor_b32_e32 v235, 0x20, v234
	v_xor_b32_e32 v236, 0x40, v234
	v_xor_b32_e32 v237, 0x60, v234
	v_readfirstlane_b32 s98, v250
	v_readfirstlane_b32 s100, v38
	v_readfirstlane_b32 s101, v39
	s_add_u32 m0, s98, 0x0
	s_nop 4
	global_load_lds_dwordx4 v244, s[100:101]
	s_add_u32 m0, s98, 0x400
	s_nop 0
	global_load_lds_dwordx4 v245, s[100:101]
	s_add_u32 m0, s98, 0x800
	s_nop 0
	global_load_lds_dwordx4 v246, s[100:101]
	s_add_u32 m0, s98, 0xc00
	s_nop 0
	global_load_lds_dwordx4 v247, s[100:101]
	v_and_b32_e32 v230, 63, v199
	v_lshlrev_b32_e32 v230, 4, v230
	v_sub_u32_e32 v230, 0, v230
	v_ashrrev_i32_e32 v231, 31, v230
	v_lshl_add_u64 v[230:231], v[40:41], 0, v[230:231]
	global_load_dwordx4 v[110:113], v[230:231], off
	global_load_dwordx4 v[106:109], v[230:231], off offset:1024
	global_load_dwordx4 v[102:105], v[230:231], off offset:2048
	global_load_dwordx4 v[98:101], v[230:231], off offset:3072
	v_readlane_b32 s12, v253, 2
	v_lshlrev_b32_e32 v167, 2, v34
	v_readlane_b32 s13, v253, 3
	v_readlane_b32 s23, v253, 13
	v_readlane_b32 s24, v253, 14
	v_readlane_b32 s25, v253, 15
	v_readlane_b32 s26, v253, 16
	v_readlane_b32 s27, v253, 17
	s_add_u32 s45, s12, s38
	v_lshlrev_b32_e32 v2, 16, v4
	v_and_b32_e32 v3, 0xffff0000, v4
	v_lshlrev_b32_e32 v4, 16, v5
	v_and_b32_e32 v5, 0xffff0000, v5
	v_lshlrev_b32_e32 v6, 16, v8
	v_and_b32_e32 v7, 0xffff0000, v8
	v_lshlrev_b32_e32 v8, 16, v9
	v_and_b32_e32 v9, 0xffff0000, v9
	v_lshlrev_b32_e32 v10, 16, v12
	v_and_b32_e32 v11, 0xffff0000, v12
	v_lshlrev_b32_e32 v12, 16, v13
	v_and_b32_e32 v13, 0xffff0000, v13
	v_lshlrev_b32_e32 v14, 16, v16
	v_and_b32_e32 v15, 0xffff0000, v16
	v_lshlrev_b32_e32 v16, 16, v17
	v_and_b32_e32 v17, 0xffff0000, v17
	v_lshlrev_b32_e32 v18, 16, v20
	v_and_b32_e32 v19, 0xffff0000, v20
	v_lshlrev_b32_e32 v20, 16, v21
	v_and_b32_e32 v21, 0xffff0000, v21
	v_lshlrev_b32_e32 v22, 16, v24
	v_and_b32_e32 v23, 0xffff0000, v24
	v_lshlrev_b32_e32 v24, 16, v25
	v_and_b32_e32 v25, 0xffff0000, v25
	v_lshlrev_b32_e32 v26, 16, v28
	v_and_b32_e32 v27, 0xffff0000, v28
	v_lshlrev_b32_e32 v28, 16, v29
	v_and_b32_e32 v29, 0xffff0000, v29
	v_lshlrev_b32_e32 v32, 16, v33
	v_and_b32_e32 v33, 0xffff0000, v33
	v_lshlrev_b32_e32 v172, 4, v35
	v_or_b32_e32 v173, 0x80, v167
	v_lshl_add_u64 v[174:175], s[66:67], 0, v[36:37]
	v_or_b32_e32 v178, s43, v159
	s_addc_u32 s46, s13, s39
	s_mov_b32 s23, 0x800000
	s_movk_i32 s24, 0xf00
	s_movk_i32 s25, 0x104
	s_mov_b64 s[26:27], 0x400c0
	v_readlane_b32 s14, v253, 4
	v_readlane_b32 s15, v253, 5
	v_readlane_b32 s16, v253, 6
	v_readlane_b32 s17, v253, 7
	v_readlane_b32 s18, v253, 8
	v_readlane_b32 s19, v253, 9
	v_readlane_b32 s20, v253, 10
	v_readlane_b32 s21, v253, 11
	v_readlane_b32 s22, v253, 12
	v_writelane_b32 v156, s38, 0
	v_writelane_b32 v156, s39, 1
	v_writelane_b32 v156, s40, 2
	v_writelane_b32 v156, s41, 3
	v_writelane_b32 v156, s42, 4
	v_writelane_b32 v156, s43, 5
	v_writelane_b32 v156, s44, 6
	v_writelane_b32 v156, s45, 7
	v_writelane_b32 v156, s46, 8
	v_writelane_b32 v156, s47, 9
	v_writelane_b32 v156, s48, 10
	v_writelane_b32 v156, s49, 11
	s_ashr_i32 s47, s30, 2
	s_and_b32 s47, s47, -8
	v_readlane_b32 s48, v254, 38
	s_add_i32 s47, s47, s48
	s_mul_hi_i32 s48, s47, 0x2aaaaaab
	s_lshr_b32 s49, s48, 31
	s_add_i32 s48, s48, s49
	s_mul_i32 s49, s48, 6
	s_sub_i32 s49, s47, s49
	s_cmp_eq_u32 s42, 0
	s_cselect_b32 s100, 4, 0
	s_lshl_b32 s101, s100, 5
	s_add_i32 s101, s101, s42
	s_add_i32 s101, s101, 0xffffff80
	s_lshl_b32 s40, s101, 7
	s_add_u32 s40, s45, s40
	s_addc_u32 s41, s46, 0
	s_lshl_b32 s48, s48, 12
	s_add_i32 s48, s48, s101
	s_mul_i32 s38, s48, 0x1c00
	s_mul_hi_u32 s39, s48, 0x1c00
	s_lshl_b32 s49, s49, 7
	s_add_i32 s49, s49, 0x300
	s_add_u32 s38, s38, s49
	s_addc_u32 s39, s39, 0
	s_add_u32 s38, s38, s66
	s_addc_u32 s39, s39, s67
	s_mov_b32 s42, s100
	v_and_b32_e32 v146, 63, v199
	v_lshrrev_b32_e32 v147, 6, v199
	v_lshrrev_b32_e32 v148, 3, v146
	v_lshl_add_u32 v148, v147, 3, v148
	v_mul_u32_u24_e32 v58, 0x1c00, v148
	v_bfe_u32 v148, v148, 1, 3
	v_and_b32_e32 v155, 7, v146
	v_xor_b32_e32 v148, v148, v155
	v_lshl_add_u32 v58, v148, 4, v58
	v_lshlrev_b32_e32 v59, 4, v199
	v_lshlrev_b32_e32 v64, 4, v146
	v_and_b32_e32 v155, 31, v146
	v_lshrrev_b32_e32 v154, 5, v146
	v_bfe_u32 v148, v155, 1, 3
	v_xor_b32_e32 v148, v148, v154
	v_lshlrev_b32_e32 v148, 4, v148
	v_lshl_add_u32 v60, v155, 7, v148
	v_xor_b32_e32 v61, 0x20, v60
	v_xor_b32_e32 v62, 0x40, v60
	v_xor_b32_e32 v63, 0x60, v60
	v_lshl_add_u32 v65, v155, 2, v147
	v_add_u32_e32 v65, 0x80, v65
	s_lshl_b32 s47, s42, 5
	v_subrev_u32_e32 v65, s47, v65
	v_lshlrev_b32_e32 v155, 2, v154
	v_mov_b32_e32 v150, 0xf149f2ca
	v_mov_b32_e32 v151, 0x80
	v_mov_b32_e32 v153, 0
	v_add_u32_e32 v34, 0, v155
	v_add_u32_e32 v35, 1, v155
	v_add_u32_e32 v36, 2, v155
	v_add_u32_e32 v37, 3, v155
	v_add_u32_e32 v38, 8, v155
	v_add_u32_e32 v39, 9, v155
	v_add_u32_e32 v40, 10, v155
	v_add_u32_e32 v41, 11, v155
	v_add_u32_e32 v42, 16, v155
	v_add_u32_e32 v43, 17, v155
	v_add_u32_e32 v44, 18, v155
	v_add_u32_e32 v45, 19, v155
	v_add_u32_e32 v46, 24, v155
	v_add_u32_e32 v47, 25, v155
	v_add_u32_e32 v48, 26, v155
	v_add_u32_e32 v49, 27, v155
	v_lshlrev_b32_e32 v147, 10, v147
	s_nop 0
	v_readfirstlane_b32 s46, v147
	s_add_u32 s46, s46, 0x8000
	s_mov_b32 s43, 0
	s_movk_i32 s44, 0x2000
	s_movk_i32 s45, 0x4000
	s_barrier
	s_add_u32 s47, s46, s43
	s_mov_b32 m0, s47
	s_nop 0
	global_load_lds_dwordx4 v58, s[38:39]
	s_add_u32 m0, s47, 0x1000
	s_nop 0
	global_load_lds_dwordx4 v59, s[40:41]
	s_add_u32 s100, s42, 1
	s_cmp_lt_u32 s100, 8
	s_cselect_b32 s48, 0x38000, 0
	s_cselect_b32 s49, 0x1000, 0
	s_add_u32 s38, s38, s48
	s_addc_u32 s39, s39, 0
	s_add_u32 s40, s40, s49
	s_addc_u32 s41, s41, 0
	s_add_u32 s47, s46, s44
	s_mov_b32 m0, s47
	s_nop 0
	global_load_lds_dwordx4 v58, s[38:39]
	s_add_u32 m0, s47, 0x1000
	s_nop 0
	global_load_lds_dwordx4 v59, s[40:41]
	s_add_u32 s100, s42, 2
	s_cmp_lt_u32 s100, 8
	s_cselect_b32 s48, 0x38000, 0
	s_cselect_b32 s49, 0x1000, 0
	s_add_u32 s38, s38, s48
	s_addc_u32 s39, s39, 0
	s_add_u32 s40, s40, s49
	s_addc_u32 s41, s41, 0

.LBB0_713:
	s_cmp_gt_i32 s47, -1
	s_cselect_b64 s[38:39], -1, 0
	s_cmp_lt_i32 s47, 0
	s_cselect_b32 s41, s44, s47
	s_cmp_lt_i32 s41, 5
	s_cselect_b64 vcc, -1, 0
	s_and_b64 s[48:49], vcc, exec
	s_cselect_b32 s48, 0xffffff80, s83
	s_cselect_b32 s49, s43, s42
	s_lshl_b32 s41, s41, 5
	s_add_i32 s41, s48, s41
	v_mov_b32_e32 v0, s46
	s_add_i32 s41, s41, s49
	v_cndmask_b32_e32 v35, v0, v171, vcc
	v_or_b32_e32 v0, s41, v159
	v_lshl_add_u32 v36, v0, 2, v158
	s_ashr_i32 s48, s41, 5
	v_cndmask_b32_e32 v36, v0, v36, vcc
	s_ashr_i32 s49, s48, 31
	v_mov_b32_e32 v34, s45
	v_ashrrev_i32_e32 v37, 31, v36
	v_cndmask_b32_e32 v34, v34, v170, vcc
	s_lshl_b64 s[48:49], s[48:49], 12
	v_lshl_add_u64 v[52:53], s[0:1], 0, v[36:37]
	v_lshl_add_u64 v[34:35], v[34:35], 0, s[48:49]
	v_mad_u64_u32 v[54:55], s[48:49], v52, s80, v[174:175]
	v_lshlrev_b32_e32 v0, 1, v172
	v_mad_i32_i24 v55, v53, s80, v55
	v_lshl_add_u64 v[50:51], v[34:35], 0, v[0:1]
	v_readfirstlane_b32 s100, v54
	v_readfirstlane_b32 s101, v55
	s_add_u32 m0, s98, 0x1000
	s_nop 4
	global_load_lds_dwordx4 v244, s[100:101]
	s_add_u32 m0, s98, 0x1400
	s_nop 0
	global_load_lds_dwordx4 v245, s[100:101]
	s_add_u32 m0, s98, 0x1800
	s_nop 0
	global_load_lds_dwordx4 v246, s[100:101]
	s_add_u32 m0, s98, 0x1c00
	s_nop 0
	global_load_lds_dwordx4 v247, s[100:101]
	v_and_b32_e32 v230, 63, v199
	v_lshlrev_b32_e32 v230, 4, v230
	v_sub_u32_e32 v230, 0, v230
	v_ashrrev_i32_e32 v231, 31, v230
	v_lshl_add_u64 v[230:231], v[50:51], 0, v[230:231]
	global_load_dwordx4 v[130:133], v[230:231], off
	global_load_dwordx4 v[122:125], v[230:231], off offset:1024
	global_load_dwordx4 v[118:121], v[230:231], off offset:2048
	global_load_dwordx4 v[114:117], v[230:231], off offset:3072
	s_waitcnt vmcnt(12)
	ds_read_b128 v[142:145], v234
	ds_read_b128 v[134:137], v235
	ds_read_b128 v[126:129], v236
	ds_read_b128 v[138:141], v237
	s_waitcnt lgkmcnt(3)
	v_mfma_f32_32x32x16_bf16 v[34:49], v[142:145], v[82:85], 0
	s_cmp_lt_u32 s44, 5
	s_cselect_b64 vcc, -1, 0
	s_and_b64 s[48:49], vcc, exec
	v_cndmask_b32_e32 v50, v166, v178, vcc
	s_cselect_b32 s41, 0x80, s58
	s_cselect_b32 s44, s43, s42
	v_add_u32_e32 v50, s41, v50
	s_waitcnt lgkmcnt(2)
	v_mfma_f32_32x32x16_bf16 v[34:49], v[134:137], v[86:89], v[34:49]
	s_add_i32 s40, s40, s44
	v_subrev_u32_e32 v50, s40, v50
	v_add_u32_e32 v51, 0xffffff7f, v50
	v_cmp_gt_u32_e32 vcc, s2, v51
	s_waitcnt lgkmcnt(1)
	v_mfma_f32_32x32x16_bf16 v[34:49], v[126:129], v[90:93], v[34:49]
	s_waitcnt lgkmcnt(0)
	v_mfma_f32_32x32x16_bf16 v[34:49], v[138:141], v[94:97], v[34:49]
	s_cbranch_vccz .LBB0_715
	v_sub_u32_e32 v50, v173, v50
	v_cmp_gt_u32_e32 vcc, s3, v50
	v_add_u32_e32 v51, 0xffffff80, v50
	s_nop 7
	v_cndmask_b32_e32 v34, v212, v34, vcc
	v_cmp_lt_u32_e32 vcc, s8, v51
	v_add_u32_e32 v51, 0xffffff81, v50
	s_nop 0
	v_cndmask_b32_e32 v35, v212, v35, vcc
	v_cmp_lt_u32_e32 vcc, s8, v51
	v_add_u32_e32 v51, 0xffffff82, v50
	s_nop 0
	v_cndmask_b32_e32 v36, v212, v36, vcc
	v_cmp_lt_u32_e32 vcc, s8, v51
	v_add_u32_e32 v51, 0xffffff87, v50
	s_nop 0
	v_cndmask_b32_e32 v37, v212, v37, vcc
	v_cmp_lt_u32_e32 vcc, s8, v51
	v_add_u32_e32 v51, 0xffffff88, v50
	s_nop 0
	v_cndmask_b32_e32 v38, v212, v38, vcc
	v_cmp_lt_u32_e32 vcc, s8, v51
	v_add_u32_e32 v51, 0xffffff89, v50
	s_nop 0
	v_cndmask_b32_e32 v39, v212, v39, vcc
	v_cmp_lt_u32_e32 vcc, s8, v51
	v_add_u32_e32 v51, 0xffffff8a, v50
	s_nop 0
	v_cndmask_b32_e32 v40, v212, v40, vcc
	v_cmp_lt_u32_e32 vcc, s8, v51
	v_add_u32_e32 v51, 0xffffff8f, v50
	s_nop 0
	v_cndmask_b32_e32 v41, v212, v41, vcc
	v_cmp_lt_u32_e32 vcc, s8, v51
	v_add_u32_e32 v51, 0xffffff90, v50
	s_nop 0
	v_cndmask_b32_e32 v42, v212, v42, vcc
	v_cmp_lt_u32_e32 vcc, s8, v51
	v_add_u32_e32 v51, 0xffffff91, v50
	s_nop 0
	v_cndmask_b32_e32 v43, v212, v43, vcc
	v_cmp_lt_u32_e32 vcc, s8, v51
	v_add_u32_e32 v51, 0xffffff92, v50
	s_nop 0
	v_cndmask_b32_e32 v44, v212, v44, vcc
	v_cmp_lt_u32_e32 vcc, s8, v51
	v_add_u32_e32 v51, 0xffffff97, v50
	s_nop 0
	v_cndmask_b32_e32 v45, v212, v45, vcc
	v_cmp_lt_u32_e32 vcc, s8, v51
	v_add_u32_e32 v51, 0xffffff98, v50
	s_nop 0
	v_cndmask_b32_e32 v46, v212, v46, vcc
	v_cmp_lt_u32_e32 vcc, s8, v51
	v_add_u32_e32 v51, 0xffffff99, v50
	v_add_u32_e32 v50, 0xffffff9a, v50
	v_cndmask_b32_e32 v47, v212, v47, vcc
	v_cmp_lt_u32_e32 vcc, s8, v51
	s_nop 1
	v_cndmask_b32_e32 v48, v212, v48, vcc
	v_cmp_lt_u32_e32 vcc, s8, v50
	s_nop 1
	v_cndmask_b32_e32 v49, v212, v49, vcc

.LBB0_722:
	s_cmp_lt_i32 s44, 0
	s_cselect_b64 s[38:39], -1, 0
	s_cmp_gt_i32 s44, -1
	s_cselect_b32 s41, s44, s47
	s_cmp_lt_i32 s41, 5
	s_cselect_b64 vcc, -1, 0
	s_and_b64 s[48:49], vcc, exec
	s_cselect_b32 s48, 0xffffff80, s83
	s_cselect_b32 s49, s43, s42
	s_lshl_b32 s41, s41, 5
	s_add_i32 s41, s48, s41
	s_add_i32 s41, s41, s49
	v_or_b32_e32 v4, s41, v159
	v_lshl_add_u32 v5, v4, 2, v158
	v_mov_b32_e32 v2, s46
	s_ashr_i32 s48, s41, 5
	v_cndmask_b32_e32 v4, v4, v5, vcc
	v_cndmask_b32_e32 v3, v2, v171, vcc
	s_ashr_i32 s49, s48, 31
	v_mov_b32_e32 v2, s45
	v_ashrrev_i32_e32 v5, 31, v4
	v_cndmask_b32_e32 v2, v2, v170, vcc
	s_lshl_b64 s[48:49], s[48:49], 12
	v_lshl_add_u64 v[4:5], s[0:1], 0, v[4:5]
	v_lshl_add_u64 v[2:3], v[2:3], 0, s[48:49]
	v_mad_u64_u32 v[6:7], s[48:49], v4, s80, v[174:175]
	v_mad_i32_i24 v7, v5, s80, v7
	v_lshl_add_u64 v[2:3], v[2:3], 0, v[0:1]
	v_readfirstlane_b32 s100, v6
	v_readfirstlane_b32 s101, v7
	s_add_u32 m0, s98, 0x0
	s_nop 4
	global_load_lds_dwordx4 v244, s[100:101]
	s_add_u32 m0, s98, 0x400
	s_nop 0
	global_load_lds_dwordx4 v245, s[100:101]
	s_add_u32 m0, s98, 0x800
	s_nop 0
	global_load_lds_dwordx4 v246, s[100:101]
	s_add_u32 m0, s98, 0xc00
	s_nop 0
	global_load_lds_dwordx4 v247, s[100:101]
	v_and_b32_e32 v230, 63, v199
	v_lshlrev_b32_e32 v230, 4, v230
	v_sub_u32_e32 v230, 0, v230
	v_ashrrev_i32_e32 v231, 31, v230
	v_lshl_add_u64 v[230:231], v[2:3], 0, v[230:231]
	global_load_dwordx4 v[110:113], v[230:231], off
	global_load_dwordx4 v[106:109], v[230:231], off offset:1024
	global_load_dwordx4 v[102:105], v[230:231], off offset:2048
	global_load_dwordx4 v[98:101], v[230:231], off offset:3072
	s_waitcnt vmcnt(12)
	ds_read_b128 v[66:69], v234 offset:4096
	ds_read_b128 v[154:157], v235 offset:4096
	ds_read_b128 v[150:153], v236 offset:4096
	ds_read_b128 v[146:149], v237 offset:4096
	s_waitcnt lgkmcnt(3)
	v_mfma_f32_32x32x16_bf16 v[66:81], v[66:69], v[82:85], 0
	s_cmp_lt_u32 s47, 5
	s_cselect_b64 vcc, -1, 0
	s_and_b64 s[48:49], vcc, exec
	v_cndmask_b32_e32 v0, v166, v178, vcc
	s_cselect_b32 s41, 0x80, s58
	s_cselect_b32 s47, s43, s42
	v_add_u32_e32 v0, s41, v0
	s_waitcnt lgkmcnt(2)
	v_mfma_f32_32x32x16_bf16 v[66:81], v[154:157], v[86:89], v[66:81]
	s_add_i32 s40, s40, s47
	v_subrev_u32_e32 v0, s40, v0
	v_add_u32_e32 v2, 0xffffff7f, v0
	v_cmp_gt_u32_e32 vcc, s2, v2
	s_waitcnt lgkmcnt(1)
	v_mfma_f32_32x32x16_bf16 v[66:81], v[150:153], v[90:93], v[66:81]
	s_waitcnt lgkmcnt(0)
	v_mfma_f32_32x32x16_bf16 v[66:81], v[146:149], v[94:97], v[66:81]
	s_cbranch_vccz .LBB0_724
	v_sub_u32_e32 v0, v173, v0
	v_cmp_gt_u32_e32 vcc, s3, v0
	v_add_u32_e32 v2, 0xffffff80, v0
	s_nop 7
	v_cndmask_b32_e32 v66, v212, v66, vcc
	v_cmp_lt_u32_e32 vcc, s8, v2
	v_add_u32_e32 v2, 0xffffff81, v0
	s_nop 0
	v_cndmask_b32_e32 v67, v212, v67, vcc
	v_cmp_lt_u32_e32 vcc, s8, v2
	v_add_u32_e32 v2, 0xffffff82, v0
	s_nop 0
	v_cndmask_b32_e32 v68, v212, v68, vcc
	v_cmp_lt_u32_e32 vcc, s8, v2
	v_add_u32_e32 v2, 0xffffff87, v0
	s_nop 0
	v_cndmask_b32_e32 v69, v212, v69, vcc
	v_cmp_lt_u32_e32 vcc, s8, v2
	v_add_u32_e32 v2, 0xffffff88, v0
	s_nop 0
	v_cndmask_b32_e32 v70, v212, v70, vcc
	v_cmp_lt_u32_e32 vcc, s8, v2
	v_add_u32_e32 v2, 0xffffff89, v0
	s_nop 0
	v_cndmask_b32_e32 v71, v212, v71, vcc
	v_cmp_lt_u32_e32 vcc, s8, v2
	v_add_u32_e32 v2, 0xffffff8a, v0
	s_nop 0
	v_cndmask_b32_e32 v72, v212, v72, vcc
	v_cmp_lt_u32_e32 vcc, s8, v2
	v_add_u32_e32 v2, 0xffffff8f, v0
	s_nop 0
	v_cndmask_b32_e32 v73, v212, v73, vcc
	v_cmp_lt_u32_e32 vcc, s8, v2
	v_add_u32_e32 v2, 0xffffff90, v0
	s_nop 0
	v_cndmask_b32_e32 v74, v212, v74, vcc
	v_cmp_lt_u32_e32 vcc, s8, v2
	v_add_u32_e32 v2, 0xffffff91, v0
	s_nop 0
	v_cndmask_b32_e32 v75, v212, v75, vcc
	v_cmp_lt_u32_e32 vcc, s8, v2
	v_add_u32_e32 v2, 0xffffff92, v0
	s_nop 0
	v_cndmask_b32_e32 v76, v212, v76, vcc
	v_cmp_lt_u32_e32 vcc, s8, v2
	v_add_u32_e32 v2, 0xffffff97, v0
	s_nop 0
	v_cndmask_b32_e32 v77, v212, v77, vcc
	v_cmp_lt_u32_e32 vcc, s8, v2
	v_add_u32_e32 v2, 0xffffff98, v0
	s_nop 0
	v_cndmask_b32_e32 v78, v212, v78, vcc
	v_cmp_lt_u32_e32 vcc, s8, v2
	v_add_u32_e32 v2, 0xffffff99, v0
	v_add_u32_e32 v0, 0xffffff9a, v0
	v_cndmask_b32_e32 v79, v212, v79, vcc
	v_cmp_lt_u32_e32 vcc, s8, v2
	s_nop 1
	v_cndmask_b32_e32 v80, v212, v80, vcc
	v_cmp_lt_u32_e32 vcc, s8, v0
	s_nop 1
	v_cndmask_b32_e32 v81, v212, v81, vcc

.LBB0_759:
	s_or_b64 exec, exec, s[40:41]
	v_ashrrev_i32_e32 v165, 31, v164
	v_readlane_b32 s48, v252, 0
	v_ashrrev_i32_e32 v167, 31, v166
	v_lshlrev_b64 v[2:3], 17, v[164:165]
	v_readlane_b32 s49, v252, 1
	v_mov_b32_e32 v0, v199
	v_lshlrev_b64 v[4:5], 13, v[166:167]
	v_lshl_add_u64 v[2:3], s[48:49], 0, v[2:3]
	v_lshl_add_u64 v[2:3], v[2:3], 0, v[4:5]
	v_lshlrev_b32_e32 v4, 5, v192
	v_and_or_b32 v0, v0, 31, v4
	s_waitcnt vmcnt(0)
	v_add_u32_e32 v4, -1, v193
	v_min_i32_e32 v4, v0, v4
	v_ashrrev_i32_e32 v5, 31, v4
	v_lshl_add_u64 v[2:3], v[4:5], 1, v[2:3]
	v_ashrrev_i32_e32 v159, 31, v158
	v_readlane_b32 s12, v252, 8
	global_load_ushort v165, v[2:3], off
	v_lshlrev_b64 v[2:3], 13, v[158:159]
	v_readlane_b32 s18, v252, 14
	v_readlane_b32 s19, v252, 15
	v_mov_b32_e32 v163, v1
	v_mov_b32_e32 v0, v199
	v_lshl_add_u64 v[2:3], s[18:19], 0, v[2:3]
	v_lshl_add_u64 v[2:3], v[162:163], 1, v[2:3]
	global_load_ushort v200, v[2:3], off
	v_ashrrev_i32_e32 v2, 2, v158
	v_ashrrev_i32_e32 v3, 31, v2
	v_lshlrev_b64 v[174:175], 12, v[2:3]
	s_and_b64 s[0:1], exec, vcc
	v_lshl_add_u64 v[172:173], v[174:175], 0, v[162:163]
	s_movk_i32 s12, 0xe00
	s_or_b64 s[44:45], s[0:1], s[44:45]
	v_mad_u64_u32 v[2:3], s[0:1], v172, s12, 0
	v_lshrrev_b32_e32 v4, 2, v0
	v_mad_i32_i24 v3, v173, s12, v3
	v_and_b32_e32 v4, 8, v4
	v_and_b32_e32 v167, 3, v158
	v_and_b32_e32 v201, 31, v0
	v_and_b32_e32 v163, 63, v0
	v_cmp_lt_i32_e32 vcc, -1, v160
	v_mov_b32_e32 v183, 0xc61c4000
	v_mov_b32_e32 v71, 0
	v_lshl_add_u64 v[170:171], v[2:3], 1, s[66:67]
	v_lshlrev_b32_e32 v168, 1, v4
	v_mov_b32_e32 v49, 0
	v_mov_b32_e32 v48, 0
	v_mov_b32_e32 v47, 0
	v_mov_b32_e32 v46, 0
	v_mov_b32_e32 v45, 0
	v_mov_b32_e32 v44, 0
	v_mov_b32_e32 v43, 0
	v_mov_b32_e32 v42, 0
	v_mov_b32_e32 v41, 0
	v_mov_b32_e32 v40, 0
	v_mov_b32_e32 v39, 0
	v_mov_b32_e32 v38, 0
	v_mov_b32_e32 v37, 0
	v_mov_b32_e32 v36, 0
	v_mov_b32_e32 v35, 0
	v_mov_b32_e32 v34, 0
	v_mov_b32_e32 v65, 0
	v_mov_b32_e32 v64, 0
	v_mov_b32_e32 v63, 0
	v_mov_b32_e32 v62, 0
	v_mov_b32_e32 v61, 0
	v_mov_b32_e32 v60, 0
	v_mov_b32_e32 v59, 0
	v_mov_b32_e32 v58, 0
	v_mov_b32_e32 v57, 0
	v_mov_b32_e32 v56, 0
	v_mov_b32_e32 v55, 0
	v_mov_b32_e32 v54, 0
	v_mov_b32_e32 v53, 0
	v_mov_b32_e32 v52, 0
	v_mov_b32_e32 v51, 0
	v_mov_b32_e32 v50, 0
	v_readlane_b32 s50, v252, 2
	v_readlane_b32 s51, v252, 3
	v_readlane_b32 s52, v252, 4
	v_readlane_b32 s53, v252, 5
	v_readlane_b32 s54, v252, 6
	v_readlane_b32 s55, v252, 7
	v_readlane_b32 s13, v252, 9
	v_readlane_b32 s14, v252, 10
	v_readlane_b32 s15, v252, 11
	v_readlane_b32 s16, v252, 12
	v_readlane_b32 s17, v252, 13
	s_and_saveexec_b64 s[0:1], vcc
	s_cbranch_execz .LBB0_775
	v_readlane_b32 s12, v253, 2
	v_lshlrev_b64 v[2:3], 19, v[158:159]
	v_readlane_b32 s22, v253, 12
	v_readlane_b32 s23, v253, 13
	v_lshlrev_b32_e32 v0, 5, v163
	v_readlane_b32 s13, v253, 3
	v_lshl_add_u64 v[2:3], s[22:23], 0, v[2:3]
	v_lshl_add_u64 v[176:177], v[2:3], 0, v[0:1]
	v_lshlrev_b32_e32 v0, 7, v167
	v_lshl_add_u64 v[4:5], v[170:171], 0, v[0:1]
	v_mov_b32_e32 v169, v1
	v_lshl_add_u64 v[4:5], v[4:5], 0, v[168:169]
	s_mov_b64 s[12:13], 0x1300
	v_lshl_add_u64 v[6:7], v[4:5], 0, s[12:13]
	v_add_co_u32_e32 v4, vcc, s97, v4
	global_load_dwordx4 v[82:85], v[6:7], off offset:64
	global_load_dwordx4 v[86:89], v[6:7], off offset:32
	v_addc_co_u32_e32 v5, vcc, 0, v5, vcc
	global_load_dwordx4 v[90:93], v[6:7], off offset:96
	global_load_dwordx4 v[94:97], v[4:5], off offset:768
	v_or_b32_e32 v6, v0, v168
	v_lshlrev_b32_e32 v0, 8, v160
	v_lshl_add_u64 v[4:5], v[174:175], 0, v[0:1]
	v_mov_b64_e32 v[2:3], s[66:67]
	v_or_b32_e32 v0, v4, v201
	v_mad_u64_u32 v[2:3], s[40:41], v0, s80, v[2:3]
	v_lshlrev_b32_e32 v184, 3, v160
	v_mad_i32_i24 v3, v5, s80, v3
	v_add_u32_e32 v0, 0x1500, v6
	v_mov_b32_e32 v185, v1
	v_lshl_add_u64 v[2:3], v[2:3], 0, v[0:1]
	v_lshlrev_b64 v[4:5], 12, v[184:185]
	v_lshl_add_u64 v[4:5], v[176:177], 0, v[4:5]
	v_and_b32_e32 v238, 63, v199
	v_lshrrev_b32_e32 v239, 3, v238
	v_and_b32_e32 v240, 31, v238
	v_lshrrev_b32_e32 v241, 5, v238
	v_and_b32_e32 v242, 7, v238
	v_lshrrev_b32_e32 v243, 4, v238
	v_xor_b32_e32 v228, v242, v243
	v_xor_b32_e32 v229, 4, v228
	v_lshlrev_b32_e32 v228, 4, v228
	v_lshlrev_b32_e32 v229, 4, v229
	v_mov_b32_e32 v224, 0x1c00
	v_mul_lo_u32 v225, v239, v224
	v_add_u32_e32 v244, v225, v228
	v_add_u32_e32 v245, 0xe000, v225
	v_add_u32_e32 v245, v245, v229
	v_add_u32_e32 v246, 0x1c000, v225
	v_add_u32_e32 v246, v246, v228
	v_add_u32_e32 v247, 0x2a000, v225
	v_add_u32_e32 v247, v247, v229
	v_lshrrev_b32_e32 v250, 6, v199
	v_lshlrev_b32_e32 v250, 13, v250
	v_bfe_u32 v251, v238, 1, 3
	v_xor_b32_e32 v251, v251, v241
	v_lshlrev_b32_e32 v251, 4, v251
	v_lshl_add_u32 v251, v240, 7, v251
	v_add_u32_e32 v234, v250, v251
	v_xor_b32_e32 v235, 0x20, v234
	v_xor_b32_e32 v236, 0x40, v234
	v_xor_b32_e32 v237, 0x60, v234
	v_readfirstlane_b32 s98, v250
	v_readfirstlane_b32 s100, v2
	v_readfirstlane_b32 s101, v3
	s_add_u32 m0, s98, 0x0
	s_nop 4
	global_load_lds_dwordx4 v244, s[100:101]
	s_add_u32 m0, s98, 0x400
	s_nop 0
	global_load_lds_dwordx4 v245, s[100:101]
	s_add_u32 m0, s98, 0x800
	s_nop 0
	global_load_lds_dwordx4 v246, s[100:101]
	s_add_u32 m0, s98, 0xc00
	s_nop 0
	global_load_lds_dwordx4 v247, s[100:101]
	v_and_b32_e32 v230, 63, v199
	v_lshlrev_b32_e32 v230, 4, v230
	v_sub_u32_e32 v230, 0, v230
	v_ashrrev_i32_e32 v231, 31, v230
	v_lshl_add_u64 v[230:231], v[4:5], 0, v[230:231]
	global_load_dwordx4 v[110:113], v[230:231], off
	global_load_dwordx4 v[106:109], v[230:231], off offset:1024
	global_load_dwordx4 v[102:105], v[230:231], off offset:2048
	global_load_dwordx4 v[98:101], v[230:231], off offset:3072
	v_mov_b32_e32 v2, v1
	v_mov_b32_e32 v3, v1
	v_mov_b32_e32 v4, v1
	v_mov_b32_e32 v5, v1
	v_mov_b32_e32 v6, v1
	v_mov_b32_e32 v7, v1
	v_mov_b32_e32 v8, v1
	v_mov_b32_e32 v9, v1
	v_mov_b32_e32 v10, v1
	v_mov_b32_e32 v11, v1
	v_mov_b32_e32 v12, v1
	v_mov_b32_e32 v13, v1
	v_mov_b32_e32 v14, v1
	v_mov_b32_e32 v15, v1
	v_mov_b32_e32 v16, v1
	v_mov_b32_e32 v17, v1
	v_mov_b32_e32 v18, v1
	v_mov_b32_e32 v19, v1
	v_mov_b32_e32 v20, v1
	v_mov_b32_e32 v21, v1
	v_mov_b32_e32 v22, v1
	v_mov_b32_e32 v23, v1
	v_mov_b32_e32 v24, v1
	v_mov_b32_e32 v25, v1
	v_mov_b32_e32 v26, v1
	v_mov_b32_e32 v27, v1
	v_mov_b32_e32 v28, v1
	v_mov_b32_e32 v29, v1
	v_mov_b32_e32 v30, v1
	v_mov_b32_e32 v31, v1
	v_lshl_add_u64 v[178:179], s[66:67], 0, v[0:1]
	v_mov_b32_e32 v0, v1
	v_mov_b64_e32 v[32:33], v[30:31]
	v_or_b32_e32 v159, 7, v184
	v_or_b32_e32 v174, v174, v201
	v_mov_b32_e32 v183, 0xc61c4000
	v_mov_b32_e32 v71, 0
	s_mov_b64 s[46:47], 0
	v_mov_b64_e32 v[30:31], v[28:29]
	v_mov_b64_e32 v[28:29], v[26:27]
	v_mov_b64_e32 v[26:27], v[24:25]
	v_mov_b64_e32 v[24:25], v[22:23]
	v_mov_b64_e32 v[22:23], v[20:21]
	v_mov_b64_e32 v[20:21], v[18:19]
	v_mov_b64_e32 v[18:19], v[16:17]
	v_mov_b64_e32 v[16:17], v[14:15]
	v_mov_b64_e32 v[14:15], v[12:13]
	v_mov_b64_e32 v[12:13], v[10:11]
	v_mov_b64_e32 v[10:11], v[8:9]
	v_mov_b64_e32 v[8:9], v[6:7]
	v_mov_b64_e32 v[6:7], v[4:5]
	v_mov_b64_e32 v[4:5], v[2:3]
	v_mov_b64_e32 v[2:3], v[0:1]
	v_readlane_b32 s14, v253, 4
	v_readlane_b32 s15, v253, 5
	v_readlane_b32 s16, v253, 6
	v_readlane_b32 s17, v253, 7
	v_readlane_b32 s18, v253, 8
	v_readlane_b32 s19, v253, 9
	v_readlane_b32 s20, v253, 10
	v_readlane_b32 s21, v253, 11
	v_readlane_b32 s24, v253, 14
	v_readlane_b32 s25, v253, 15
	v_readlane_b32 s26, v253, 16
	v_readlane_b32 s27, v253, 17
	s_branch .LBB0_764

.LBB0_764:
	v_add_u32_e32 v0, 1, v184
	v_cmp_lt_i32_e32 vcc, v184, v159
	s_nop 1
	v_cndmask_b32_e32 v182, -1, v0, vcc
	v_cmp_gt_i32_e32 vcc, 0, v182
	s_nop 1
	v_cndmask_b32_e32 v50, v182, v184, vcc
	v_lshlrev_b32_e32 v34, 5, v50
	v_ashrrev_i32_e32 v35, 31, v34
	v_lshl_add_u64 v[52:53], v[174:175], 0, v[34:35]
	v_mad_u64_u32 v[54:55], s[40:41], v52, s80, v[178:179]
	v_mov_b32_e32 v0, v55
	v_mad_u64_u32 v[52:53], s[40:41], v53, s80, v[0:1]
	v_ashrrev_i32_e32 v51, 31, v50
	v_mov_b32_e32 v55, v52
	v_lshlrev_b64 v[50:51], 12, v[50:51]
	v_lshl_add_u64 v[50:51], v[176:177], 0, v[50:51]
	v_readfirstlane_b32 s100, v54
	v_readfirstlane_b32 s101, v55
	s_add_u32 m0, s98, 0x1000
	s_nop 4
	global_load_lds_dwordx4 v244, s[100:101]
	s_add_u32 m0, s98, 0x1400
	s_nop 0
	global_load_lds_dwordx4 v245, s[100:101]
	s_add_u32 m0, s98, 0x1800
	s_nop 0
	global_load_lds_dwordx4 v246, s[100:101]
	s_add_u32 m0, s98, 0x1c00
	s_nop 0
	global_load_lds_dwordx4 v247, s[100:101]
	v_and_b32_e32 v230, 63, v199
	v_lshlrev_b32_e32 v230, 4, v230
	v_sub_u32_e32 v230, 0, v230
	v_ashrrev_i32_e32 v231, 31, v230
	v_lshl_add_u64 v[230:231], v[50:51], 0, v[230:231]
	global_load_dwordx4 v[126:129], v[230:231], off
	global_load_dwordx4 v[122:125], v[230:231], off offset:1024
	global_load_dwordx4 v[118:121], v[230:231], off offset:2048
	global_load_dwordx4 v[114:117], v[230:231], off offset:3072
	s_waitcnt vmcnt(12)
	ds_read_b128 v[142:145], v234
	ds_read_b128 v[134:137], v235
	ds_read_b128 v[130:133], v236
	ds_read_b128 v[138:141], v237
	s_waitcnt lgkmcnt(3)
	v_mfma_f32_32x32x16_bf16 v[34:49], v[142:145], v[94:97], 0
	v_cmp_lt_i32_e64 s[40:41], -1, v182
	s_waitcnt lgkmcnt(2)
	v_mfma_f32_32x32x16_bf16 v[34:49], v[134:137], v[86:89], v[34:49]
	s_waitcnt lgkmcnt(1)
	v_mfma_f32_32x32x16_bf16 v[34:49], v[130:133], v[82:85], v[34:49]
	s_waitcnt lgkmcnt(0)
	v_mfma_f32_32x32x16_bf16 v[34:49], v[138:141], v[90:93], v[34:49]
	s_nop 11
	v_max3_f32 v0, v34, v35, v36
	v_max3_f32 v50, v37, v38, v39
	v_max3_f32 v51, v40, v41, v42
	v_max3_f32 v52, v43, v44, v45
	v_max3_f32 v53, v46, v47, v48
	v_max3_f32 v0, v0, v50, v49
	v_max3_f32 v51, v51, v52, v53
	v_max_f32_e32 v0, v0, v51
	v_mov_b32_e32 v50, v0
	s_nop 1
	v_permlane32_swap_b32_e32 v0, v50
	v_max_f32_e32 v0, v0, v50
	v_add_f32_e32 v50, 0x41800000, v183
	v_cmp_gt_f32_e32 vcc, v0, v50
	s_cbranch_vccz .LBB0_766
	s_nop 0
	v_cndmask_b32_e32 v180, v183, v0, vcc
	v_sub_f32_e32 v0, v183, v180
	v_exp_f32_e32 v0, v0
	s_nop 0
	v_mul_f32_e32 v71, v71, v0
	v_pk_mul_f32 v[32:33], v[32:33], v[0:1] op_sel_hi:[1,0]
	v_pk_mul_f32 v[30:31], v[30:31], v[0:1] op_sel_hi:[1,0]
	v_pk_mul_f32 v[28:29], v[28:29], v[0:1] op_sel_hi:[1,0]
	v_pk_mul_f32 v[26:27], v[26:27], v[0:1] op_sel_hi:[1,0]
	v_pk_mul_f32 v[24:25], v[24:25], v[0:1] op_sel_hi:[1,0]
	v_pk_mul_f32 v[22:23], v[22:23], v[0:1] op_sel_hi:[1,0]
	v_pk_mul_f32 v[20:21], v[20:21], v[0:1] op_sel_hi:[1,0]
	v_pk_mul_f32 v[18:19], v[18:19], v[0:1] op_sel_hi:[1,0]
	v_pk_mul_f32 v[16:17], v[16:17], v[0:1] op_sel_hi:[1,0]
	v_pk_mul_f32 v[14:15], v[14:15], v[0:1] op_sel_hi:[1,0]
	v_pk_mul_f32 v[12:13], v[12:13], v[0:1] op_sel_hi:[1,0]
	v_pk_mul_f32 v[10:11], v[10:11], v[0:1] op_sel_hi:[1,0]
	v_pk_mul_f32 v[8:9], v[8:9], v[0:1] op_sel_hi:[1,0]
	v_pk_mul_f32 v[6:7], v[6:7], v[0:1] op_sel_hi:[1,0]
	v_pk_mul_f32 v[4:5], v[4:5], v[0:1] op_sel_hi:[1,0]
	v_pk_mul_f32 v[2:3], v[2:3], v[0:1] op_sel_hi:[1,0]
	s_branch .LBB0_767

.LBB0_767:
	v_pk_add_f32 v[34:35], v[34:35], v[180:181] op_sel_hi:[1,0] neg_lo:[0,1] neg_hi:[0,1]
	v_pk_add_f32 v[36:37], v[36:37], v[180:181] op_sel_hi:[1,0] neg_lo:[0,1] neg_hi:[0,1]
	v_exp_f32_e32 v50, v34
	v_exp_f32_e32 v51, v35
	v_exp_f32_e32 v52, v36
	v_exp_f32_e32 v53, v37
	v_pk_add_f32 v[36:37], v[38:39], v[180:181] op_sel_hi:[1,0] neg_lo:[0,1] neg_hi:[0,1]
	v_pk_add_f32 v[34:35], v[50:51], 0 op_sel_hi:[1,0]
	v_exp_f32_e32 v38, v36
	v_exp_f32_e32 v39, v37
	v_pk_add_f32 v[36:37], v[40:41], v[180:181] op_sel_hi:[1,0] neg_lo:[0,1] neg_hi:[0,1]
	v_pk_add_f32 v[40:41], v[42:43], v[180:181] op_sel_hi:[1,0] neg_lo:[0,1] neg_hi:[0,1]
	v_exp_f32_e32 v36, v36
	v_exp_f32_e32 v37, v37
	v_exp_f32_e32 v40, v40
	v_exp_f32_e32 v41, v41
	v_pk_add_f32 v[42:43], v[44:45], v[180:181] op_sel_hi:[1,0] neg_lo:[0,1] neg_hi:[0,1]
	v_pk_add_f32 v[34:35], v[52:53], v[34:35]
	v_exp_f32_e32 v42, v42
	v_exp_f32_e32 v43, v43
	v_pk_add_f32 v[44:45], v[46:47], v[180:181] op_sel_hi:[1,0] neg_lo:[0,1] neg_hi:[0,1]
	v_pk_add_f32 v[34:35], v[38:39], v[34:35]
	v_exp_f32_e32 v44, v44
	v_exp_f32_e32 v45, v45
	v_pk_add_f32 v[46:47], v[48:49], v[180:181] op_sel_hi:[1,0] neg_lo:[0,1] neg_hi:[0,1]
	v_pk_add_f32 v[34:35], v[36:37], v[34:35]
	v_exp_f32_e32 v46, v46
	v_exp_f32_e32 v47, v47
	v_pk_add_f32 v[34:35], v[40:41], v[34:35]
	v_cvt_pk_bf16_f32 v37, v36, v37
	v_pk_add_f32 v[34:35], v[42:43], v[34:35]
	v_cvt_pk_bf16_f32 v36, v38, v39
	v_pk_add_f32 v[34:35], v[44:45], v[34:35]
	v_cvt_pk_bf16_f32 v73, v46, v47
	v_pk_add_f32 v[34:35], v[46:47], v[34:35]
	v_cvt_pk_bf16_f32 v72, v44, v45
	v_pk_add_f32 v[34:35], v[34:35], v[34:35] op_sel:[0,1] op_sel_hi:[1,0]
	v_cvt_pk_bf16_f32 v70, v40, v41
	v_mov_b32_e32 v0, v34
	s_nop 1
	v_permlane32_swap_b32_e32 v34, v0
	v_add_f32_e32 v0, v34, v0
	v_cvt_pk_bf16_f32 v35, v52, v53
	v_cvt_pk_bf16_f32 v34, v50, v51
	v_add_f32_e32 v169, v71, v0
	v_cvt_pk_bf16_f32 v71, v42, v43
	s_waitcnt vmcnt(11)
	v_mfma_f32_32x32x16_bf16 v[2:17], v[110:113], v[34:37], v[2:17]
	s_mov_b64 s[54:55], -1
	s_or_b64 s[50:51], s[50:51], exec
	s_waitcnt vmcnt(9)
	v_mfma_f32_32x32x16_bf16 v[18:33], v[102:105], v[34:37], v[18:33]
	s_nop 7
	v_mov_b64_e32 v[64:65], v[16:17]
	v_mov_b64_e32 v[62:63], v[14:15]
	v_mov_b64_e32 v[60:61], v[12:13]
	v_mov_b64_e32 v[58:59], v[10:11]
	v_mov_b64_e32 v[56:57], v[8:9]
	v_mov_b64_e32 v[54:55], v[6:7]
	v_mov_b64_e32 v[52:53], v[4:5]
	v_mov_b64_e32 v[48:49], v[32:33]
	v_mov_b64_e32 v[50:51], v[2:3]
	v_mov_b64_e32 v[46:47], v[30:31]
	v_mov_b64_e32 v[44:45], v[28:29]
	v_mov_b64_e32 v[42:43], v[26:27]
	v_mov_b64_e32 v[40:41], v[24:25]
	v_mov_b64_e32 v[38:39], v[22:23]
	v_mov_b64_e32 v[36:37], v[20:21]
	v_mov_b64_e32 v[34:35], v[18:19]
	v_mfma_f32_32x32x16_bf16 v[50:65], v[106:109], v[70:73], v[50:65]
	s_waitcnt vmcnt(8)
	v_mfma_f32_32x32x16_bf16 v[34:49], v[98:101], v[70:73], v[34:49]
	s_and_saveexec_b64 s[52:53], s[40:41]
	s_cbranch_execz .LBB0_763
	v_add_u32_e32 v184, 1, v182
	v_cmp_lt_u32_e32 vcc, v182, v159
	v_mov_b32_e32 v3, v1
	s_waitcnt vmcnt(4)
	ds_read_b128 v[66:69], v234 offset:4096
	ds_read_b128 v[154:157], v235 offset:4096
	ds_read_b128 v[150:153], v236 offset:4096
	ds_read_b128 v[146:149], v237 offset:4096
	s_waitcnt lgkmcnt(3)
	v_mfma_f32_32x32x16_bf16 v[66:81], v[66:69], v[94:97], 0
	v_cndmask_b32_e32 v2, v182, v184, vcc
	v_lshlrev_b32_e32 v0, 5, v2
	v_lshl_add_u64 v[4:5], v[174:175], 0, v[0:1]
	v_mad_u64_u32 v[6:7], s[40:41], v4, s80, v[178:179]
	v_mov_b32_e32 v0, v7
	v_mad_u64_u32 v[4:5], s[40:41], v5, s80, v[0:1]
	v_mov_b32_e32 v7, v4
	v_lshlrev_b64 v[2:3], 12, v[2:3]
	v_lshl_add_u64 v[2:3], v[176:177], 0, v[2:3]
	v_readfirstlane_b32 s100, v6
	v_readfirstlane_b32 s101, v7
	s_add_u32 m0, s98, 0x0
	s_nop 4
	global_load_lds_dwordx4 v244, s[100:101]
	s_add_u32 m0, s98, 0x400
	s_nop 0
	global_load_lds_dwordx4 v245, s[100:101]
	s_add_u32 m0, s98, 0x800
	s_nop 0
	global_load_lds_dwordx4 v246, s[100:101]
	s_add_u32 m0, s98, 0xc00
	s_nop 0
	global_load_lds_dwordx4 v247, s[100:101]
	v_and_b32_e32 v230, 63, v199
	v_lshlrev_b32_e32 v230, 4, v230
	v_sub_u32_e32 v230, 0, v230
	v_ashrrev_i32_e32 v231, 31, v230
	v_lshl_add_u64 v[230:231], v[2:3], 0, v[230:231]
	global_load_dwordx4 v[110:113], v[230:231], off
	global_load_dwordx4 v[106:109], v[230:231], off offset:1024
	global_load_dwordx4 v[102:105], v[230:231], off offset:2048
	global_load_dwordx4 v[98:101], v[230:231], off offset:3072
	s_waitcnt lgkmcnt(2)
	v_mfma_f32_32x32x16_bf16 v[66:81], v[154:157], v[86:89], v[66:81]
	v_cmp_ge_u32_e64 s[40:41], v182, v159
	s_waitcnt lgkmcnt(1)
	v_mfma_f32_32x32x16_bf16 v[66:81], v[150:153], v[82:85], v[66:81]
	s_waitcnt lgkmcnt(0)
	v_mfma_f32_32x32x16_bf16 v[66:81], v[146:149], v[90:93], v[66:81]
	s_nop 11
	v_max3_f32 v0, v66, v67, v68
	v_max3_f32 v2, v69, v70, v71
	v_max3_f32 v3, v72, v73, v74
	v_max3_f32 v4, v75, v76, v77
	v_max3_f32 v5, v78, v79, v80
	v_max3_f32 v0, v0, v2, v81
	v_max3_f32 v3, v3, v4, v5
	v_max_f32_e32 v0, v0, v3
	v_mov_b32_e32 v2, v0
	s_nop 1
	v_permlane32_swap_b32_e32 v0, v2
	v_max_f32_e32 v0, v0, v2
	v_add_f32_e32 v2, 0x41800000, v180
	v_cmp_gt_f32_e32 vcc, v0, v2
	s_cbranch_vccnz .LBB0_761
	v_mov_b64_e32 v[182:183], v[180:181]
	v_mov_b32_e32 v0, v169
	v_mov_b32_e32 v183, v180
	v_mov_b32_e32 v2, v50
	v_mov_b32_e32 v3, v51
	v_mov_b32_e32 v4, v52
	v_mov_b32_e32 v5, v53
	v_mov_b32_e32 v6, v54
	v_mov_b32_e32 v7, v55
	v_mov_b32_e32 v8, v56
	v_mov_b32_e32 v9, v57
	v_mov_b32_e32 v10, v58
	v_mov_b32_e32 v11, v59
	v_mov_b32_e32 v12, v60
	v_mov_b32_e32 v13, v61
	v_mov_b32_e32 v14, v62
	v_mov_b32_e32 v15, v63
	v_mov_b32_e32 v16, v64
	v_mov_b32_e32 v17, v65
	v_mov_b32_e32 v18, v34
	v_mov_b32_e32 v19, v35
	v_mov_b32_e32 v20, v36
	v_mov_b32_e32 v21, v37
	v_mov_b32_e32 v22, v38
	v_mov_b32_e32 v23, v39
	v_mov_b32_e32 v24, v40
	v_mov_b32_e32 v25, v41
	v_mov_b32_e32 v26, v42
	v_mov_b32_e32 v27, v43
	v_mov_b32_e32 v28, v44
	v_mov_b32_e32 v29, v45
	v_mov_b32_e32 v30, v46
	v_mov_b32_e32 v31, v47
	v_mov_b32_e32 v32, v48
	v_mov_b32_e32 v33, v49
	s_branch .LBB0_762

.LBB0_849:
	s_or_b64 exec, exec, s[44:45]
	v_cmp_lt_i32_e32 vcc, -1, v162
	v_lshlrev_b32_e32 v0, 2, v39
	s_and_saveexec_b64 s[38:39], vcc
	s_xor_b64 s[40:41], exec, s[38:39]
	s_cbranch_execz .LBB0_846
	v_readlane_b32 s12, v253, 2
	v_and_b32_e32 v0, 63, v35
	s_lshl_b64 s[38:39], s[42:43], 19
	v_readlane_b32 s22, v253, 12
	v_mov_b32_e32 v35, v1
	v_readlane_b32 s23, v253, 13
	s_add_u32 s38, s22, s38
	v_lshl_add_u64 v[34:35], s[0:1], 0, v[34:35]
	s_addc_u32 s39, s23, s39
	v_lshlrev_b32_e32 v0, 5, v0
	v_readlane_b32 s12, v254, 43
	v_or_b32_e32 v34, v34, v38
	v_mov_b64_e32 v[36:37], s[66:67]
	v_lshl_add_u64 v[166:167], s[38:39], 0, v[0:1]
	v_or_b32_e32 v0, s12, v40
	v_mad_u64_u32 v[36:37], s[38:39], v34, s80, v[36:37]
	v_mad_i32_i24 v37, v35, s80, v37
	v_lshlrev_b32_e32 v34, 1, v0
	v_mov_b32_e32 v35, v1
	v_mov_b32_e32 v163, v1
	v_lshl_add_u64 v[36:37], v[36:37], 0, v[34:35]
	v_lshlrev_b64 v[40:41], 12, v[162:163]
	v_lshl_add_u64 v[40:41], v[166:167], 0, v[40:41]
	v_and_b32_e32 v238, 63, v199
	v_lshrrev_b32_e32 v239, 3, v238
	v_and_b32_e32 v240, 31, v238
	v_lshrrev_b32_e32 v241, 5, v238
	v_and_b32_e32 v242, 7, v238
	v_lshrrev_b32_e32 v243, 4, v238
	v_xor_b32_e32 v228, v242, v243
	v_xor_b32_e32 v229, 4, v228
	v_lshlrev_b32_e32 v228, 4, v228
	v_lshlrev_b32_e32 v229, 4, v229
	v_mov_b32_e32 v224, 0x1c00
	v_mul_lo_u32 v225, v239, v224
	v_add_u32_e32 v244, v225, v228
	v_add_u32_e32 v245, 0xe000, v225
	v_add_u32_e32 v245, v245, v229
	v_add_u32_e32 v246, 0x1c000, v225
	v_add_u32_e32 v246, v246, v228
	v_add_u32_e32 v247, 0x2a000, v225
	v_add_u32_e32 v247, v247, v229
	v_lshrrev_b32_e32 v250, 6, v199
	v_lshlrev_b32_e32 v250, 13, v250
	v_bfe_u32 v251, v238, 1, 3
	v_xor_b32_e32 v251, v251, v241
	v_lshlrev_b32_e32 v251, 4, v251
	v_lshl_add_u32 v251, v240, 7, v251
	v_add_u32_e32 v234, v250, v251
	v_xor_b32_e32 v235, 0x20, v234
	v_xor_b32_e32 v236, 0x40, v234
	v_xor_b32_e32 v237, 0x60, v234
	v_readfirstlane_b32 s98, v250
	v_readfirstlane_b32 s100, v36
	v_readfirstlane_b32 s101, v37
	s_add_u32 m0, s98, 0x0
	s_nop 4
	global_load_lds_dwordx4 v244, s[100:101]
	s_add_u32 m0, s98, 0x400
	s_nop 0
	global_load_lds_dwordx4 v245, s[100:101]
	s_add_u32 m0, s98, 0x800
	s_nop 0
	global_load_lds_dwordx4 v246, s[100:101]
	s_add_u32 m0, s98, 0xc00
	s_nop 0
	global_load_lds_dwordx4 v247, s[100:101]
	v_and_b32_e32 v230, 63, v199
	v_lshlrev_b32_e32 v230, 4, v230
	v_sub_u32_e32 v230, 0, v230
	v_ashrrev_i32_e32 v231, 31, v230
	v_lshl_add_u64 v[230:231], v[40:41], 0, v[230:231]
	global_load_dwordx4 v[110:113], v[230:231], off
	global_load_dwordx4 v[106:109], v[230:231], off offset:1024
	global_load_dwordx4 v[102:105], v[230:231], off offset:2048
	global_load_dwordx4 v[98:101], v[230:231], off offset:3072
	v_lshl_add_u64 v[170:171], s[66:67], 0, v[34:35]
	v_and_b32_e32 v34, 0x7ffffff8, v162
	v_lshlrev_b32_e32 v0, 2, v39
	v_cmp_ne_u32_e32 vcc, v34, v162
	v_or_b32_e32 v163, 0x186a0, v0
	v_or_b32_e32 v172, 0x186a1, v0
	v_or_b32_e32 v173, 0x186a2, v0
	v_or_b32_e32 v174, 0x186a3, v0
	v_or_b32_e32 v175, 0x186a8, v0
	v_or_b32_e32 v176, 0x186a9, v0
	v_or_b32_e32 v177, 0x186aa, v0
	v_or_b32_e32 v178, 0x186ab, v0
	v_or_b32_e32 v179, 0x186b0, v0
	v_or_b32_e32 v180, 0x186b1, v0
	v_or_b32_e32 v181, 0x186b2, v0
	v_or_b32_e32 v182, 0x186b3, v0
	v_or_b32_e32 v183, 0x186b8, v0
	v_or_b32_e32 v184, 0x186b9, v0
	v_or_b32_e32 v185, 0x186ba, v0
	v_or_b32_e32 v186, 0x186bb, v0
	v_or_b32_e32 v168, s0, v38
	v_mov_b32_e32 v169, s1
	v_or_b32_e32 v187, 0x186a0, v38
	v_cndmask_b32_e32 v188, -1, v34, vcc
	s_mov_b64 s[44:45], 0
	v_mov_b32_e32 v190, v162
	v_readlane_b32 s13, v253, 3
	v_readlane_b32 s14, v253, 4
	v_readlane_b32 s15, v253, 5
	v_readlane_b32 s16, v253, 6
	v_readlane_b32 s17, v253, 7
	v_readlane_b32 s18, v253, 8
	v_readlane_b32 s19, v253, 9
	v_readlane_b32 s20, v253, 10
	v_readlane_b32 s21, v253, 11
	v_readlane_b32 s24, v253, 14
	v_readlane_b32 s25, v253, 15
	v_readlane_b32 s26, v253, 16
	v_readlane_b32 s27, v253, 17
	s_branch .LBB0_854

.LBB0_854:
	v_add_u32_e32 v34, 1, v190
	v_cmp_lt_i32_e32 vcc, v34, v162
	s_nop 1
	v_cndmask_b32_e32 v34, -1, v34, vcc
	v_cmp_eq_u32_e32 vcc, v190, v162
	s_nop 1
	v_cndmask_b32_e32 v71, v34, v188, vcc
	v_cmp_gt_i32_e64 s[0:1], 0, v71
	v_cmp_lt_i32_e64 s[38:39], -1, v71
	s_nop 0
	v_cndmask_b32_e64 v50, v71, v190, s[0:1]
	v_lshlrev_b32_e32 v34, 5, v50
	v_ashrrev_i32_e32 v35, 31, v34
	v_lshl_add_u64 v[52:53], v[168:169], 0, v[34:35]
	v_mad_u64_u32 v[54:55], s[0:1], v52, s80, v[170:171]
	v_mov_b32_e32 v52, v55
	v_mad_u64_u32 v[52:53], s[0:1], v53, s80, v[52:53]
	v_ashrrev_i32_e32 v51, 31, v50
	v_mov_b32_e32 v55, v52
	v_lshlrev_b64 v[50:51], 12, v[50:51]
	v_lshl_add_u64 v[50:51], v[166:167], 0, v[50:51]
	v_readfirstlane_b32 s100, v54
	v_readfirstlane_b32 s101, v55
	s_add_u32 m0, s98, 0x1000
	s_nop 4
	global_load_lds_dwordx4 v244, s[100:101]
	s_add_u32 m0, s98, 0x1400
	s_nop 0
	global_load_lds_dwordx4 v245, s[100:101]
	s_add_u32 m0, s98, 0x1800
	s_nop 0
	global_load_lds_dwordx4 v246, s[100:101]
	s_add_u32 m0, s98, 0x1c00
	s_nop 0
	global_load_lds_dwordx4 v247, s[100:101]
	v_and_b32_e32 v230, 63, v199
	v_lshlrev_b32_e32 v230, 4, v230
	v_sub_u32_e32 v230, 0, v230
	v_ashrrev_i32_e32 v231, 31, v230
	v_lshl_add_u64 v[230:231], v[50:51], 0, v[230:231]
	global_load_dwordx4 v[142:145], v[230:231], off
	global_load_dwordx4 v[126:129], v[230:231], off offset:1024
	global_load_dwordx4 v[118:121], v[230:231], off offset:2048
	global_load_dwordx4 v[114:117], v[230:231], off offset:3072
	s_waitcnt vmcnt(12)
	ds_read_b128 v[138:141], v234
	ds_read_b128 v[130:133], v235
	ds_read_b128 v[122:125], v236
	ds_read_b128 v[134:137], v237
	s_waitcnt lgkmcnt(3)
	v_mfma_f32_32x32x16_bf16 v[34:49], v[138:141], v[90:93], 0
	v_cndmask_b32_e32 v50, v219, v187, vcc
	v_cmp_gt_u32_e32 vcc, s9, v50
	s_waitcnt lgkmcnt(2)
	v_mfma_f32_32x32x16_bf16 v[34:49], v[130:133], v[82:85], v[34:49]
	s_waitcnt lgkmcnt(1)
	v_mfma_f32_32x32x16_bf16 v[34:49], v[122:125], v[86:89], v[34:49]
	s_waitcnt lgkmcnt(0)
	v_mfma_f32_32x32x16_bf16 v[34:49], v[134:137], v[94:97], v[34:49]
	s_cbranch_vccz .LBB0_856
	v_cmp_le_u32_e32 vcc, v163, v50
	s_nop 9
	v_cndmask_b32_e32 v34, v212, v34, vcc
	v_cmp_le_u32_e32 vcc, v172, v50
	s_nop 1
	v_cndmask_b32_e32 v35, v212, v35, vcc
	v_cmp_le_u32_e32 vcc, v173, v50
	s_nop 1
	v_cndmask_b32_e32 v36, v212, v36, vcc
	v_cmp_le_u32_e32 vcc, v174, v50
	s_nop 1
	v_cndmask_b32_e32 v37, v212, v37, vcc
	v_cmp_le_u32_e32 vcc, v175, v50
	s_nop 1
	v_cndmask_b32_e32 v38, v212, v38, vcc
	v_cmp_le_u32_e32 vcc, v176, v50
	s_nop 1
	v_cndmask_b32_e32 v39, v212, v39, vcc
	v_cmp_le_u32_e32 vcc, v177, v50
	s_nop 1
	v_cndmask_b32_e32 v40, v212, v40, vcc
	v_cmp_le_u32_e32 vcc, v178, v50
	s_nop 1
	v_cndmask_b32_e32 v41, v212, v41, vcc
	v_cmp_le_u32_e32 vcc, v179, v50
	s_nop 1
	v_cndmask_b32_e32 v42, v212, v42, vcc
	v_cmp_le_u32_e32 vcc, v180, v50
	s_nop 1
	v_cndmask_b32_e32 v43, v212, v43, vcc
	v_cmp_le_u32_e32 vcc, v181, v50
	s_nop 1
	v_cndmask_b32_e32 v44, v212, v44, vcc
	v_cmp_le_u32_e32 vcc, v182, v50
	s_nop 1
	v_cndmask_b32_e32 v45, v212, v45, vcc
	v_cmp_le_u32_e32 vcc, v183, v50
	s_nop 1
	v_cndmask_b32_e32 v46, v212, v46, vcc
	v_cmp_le_u32_e32 vcc, v184, v50
	s_nop 1
	v_cndmask_b32_e32 v47, v212, v47, vcc
	v_cmp_le_u32_e32 vcc, v185, v50
	s_nop 1
	v_cndmask_b32_e32 v48, v212, v48, vcc
	v_cmp_le_u32_e32 vcc, v186, v50
	s_nop 1
	v_cndmask_b32_e32 v49, v212, v49, vcc

.LBB0_858:
	v_pk_add_f32 v[34:35], v[34:35], v[164:165] op_sel_hi:[1,0] neg_lo:[0,1] neg_hi:[0,1]
	v_pk_add_f32 v[36:37], v[36:37], v[164:165] op_sel_hi:[1,0] neg_lo:[0,1] neg_hi:[0,1]
	v_exp_f32_e32 v34, v34
	v_exp_f32_e32 v35, v35
	v_exp_f32_e32 v36, v36
	v_exp_f32_e32 v37, v37
	v_pk_add_f32 v[38:39], v[38:39], v[164:165] op_sel_hi:[1,0] neg_lo:[0,1] neg_hi:[0,1]
	v_pk_add_f32 v[40:41], v[40:41], v[164:165] op_sel_hi:[1,0] neg_lo:[0,1] neg_hi:[0,1]
	v_exp_f32_e32 v38, v38
	v_exp_f32_e32 v39, v39
	v_exp_f32_e32 v40, v40
	v_exp_f32_e32 v41, v41
	v_pk_add_f32 v[42:43], v[42:43], v[164:165] op_sel_hi:[1,0] neg_lo:[0,1] neg_hi:[0,1]
	v_pk_add_f32 v[50:51], v[34:35], 0 op_sel_hi:[1,0]
	v_exp_f32_e32 v42, v42
	v_exp_f32_e32 v43, v43
	v_pk_add_f32 v[44:45], v[44:45], v[164:165] op_sel_hi:[1,0] neg_lo:[0,1] neg_hi:[0,1]
	v_pk_add_f32 v[50:51], v[36:37], v[50:51]
	v_exp_f32_e32 v44, v44
	v_exp_f32_e32 v45, v45
	v_pk_add_f32 v[46:47], v[46:47], v[164:165] op_sel_hi:[1,0] neg_lo:[0,1] neg_hi:[0,1]
	v_pk_add_f32 v[50:51], v[38:39], v[50:51]
	v_exp_f32_e32 v46, v46
	v_exp_f32_e32 v47, v47
	v_pk_add_f32 v[48:49], v[48:49], v[164:165] op_sel_hi:[1,0] neg_lo:[0,1] neg_hi:[0,1]
	v_pk_add_f32 v[50:51], v[40:41], v[50:51]
	v_exp_f32_e32 v48, v48
	v_exp_f32_e32 v49, v49
	v_pk_add_f32 v[50:51], v[42:43], v[50:51]
	v_cvt_pk_bf16_f32 v53, v40, v41
	v_pk_add_f32 v[50:51], v[44:45], v[50:51]
	v_cvt_pk_bf16_f32 v52, v38, v39
	v_pk_add_f32 v[50:51], v[46:47], v[50:51]
	v_cvt_pk_bf16_f32 v75, v48, v49
	v_pk_add_f32 v[50:51], v[48:49], v[50:51]
	v_cvt_pk_bf16_f32 v74, v46, v47
	v_pk_add_f32 v[50:51], v[50:51], v[50:51] op_sel:[0,1] op_sel_hi:[1,0]
	v_cvt_pk_bf16_f32 v73, v44, v45
	v_mov_b32_e32 v51, v50
	s_nop 1
	v_permlane32_swap_b32_e32 v50, v51
	v_add_f32_e32 v50, v50, v51
	v_add_f32_e32 v189, v70, v50
	v_cvt_pk_bf16_f32 v51, v36, v37
	v_cvt_pk_bf16_f32 v50, v34, v35
	v_cvt_pk_bf16_f32 v72, v42, v43
	s_mov_b64 s[0:1], -1
	s_waitcnt vmcnt(11)
	v_mfma_f32_32x32x16_bf16 v[18:33], v[110:113], v[50:53], v[18:33]
	s_or_b64 s[46:47], s[46:47], exec
	s_waitcnt vmcnt(9)
	v_mfma_f32_32x32x16_bf16 v[2:17], v[102:105], v[50:53], v[2:17]
	s_nop 8
	v_mov_b64_e32 v[48:49], v[32:33]
	v_mov_b64_e32 v[46:47], v[30:31]
	v_mov_b64_e32 v[44:45], v[28:29]
	v_mov_b64_e32 v[42:43], v[26:27]
	v_mov_b64_e32 v[40:41], v[24:25]
	v_mov_b64_e32 v[38:39], v[22:23]
	v_mov_b64_e32 v[36:37], v[20:21]
	v_mov_b64_e32 v[64:65], v[16:17]
	v_mov_b64_e32 v[34:35], v[18:19]
	v_mov_b64_e32 v[62:63], v[14:15]
	v_mov_b64_e32 v[60:61], v[12:13]
	v_mov_b64_e32 v[58:59], v[10:11]
	v_mov_b64_e32 v[56:57], v[8:9]
	v_mov_b64_e32 v[54:55], v[6:7]
	v_mov_b64_e32 v[52:53], v[4:5]
	v_mov_b64_e32 v[50:51], v[2:3]
	v_mfma_f32_32x32x16_bf16 v[34:49], v[106:109], v[72:75], v[34:49]
	s_waitcnt vmcnt(8)
	v_mfma_f32_32x32x16_bf16 v[50:65], v[98:101], v[72:75], v[50:65]
	s_and_saveexec_b64 s[48:49], s[38:39]
	s_cbranch_execz .LBB0_853
	v_add_u32_e32 v2, 1, v71
	v_cmp_lt_i32_e32 vcc, v2, v162
	s_nop 1
	v_cndmask_b32_e32 v2, -1, v2, vcc
	v_cmp_eq_u32_e32 vcc, v71, v162
	s_nop 1
	v_cndmask_b32_e32 v190, v2, v188, vcc
	v_cmp_lt_i32_e64 s[0:1], -1, v190
	v_cmp_gt_i32_e64 s[38:39], 0, v190
	s_nop 0
	v_cndmask_b32_e64 v2, v71, v190, s[0:1]
	v_lshlrev_b32_e32 v4, 5, v2
	v_ashrrev_i32_e32 v5, 31, v4
	v_lshl_add_u64 v[4:5], v[168:169], 0, v[4:5]
	v_mad_u64_u32 v[6:7], s[0:1], v4, s80, v[170:171]
	v_mov_b32_e32 v4, v7
	v_mad_u64_u32 v[4:5], s[0:1], v5, s80, v[4:5]
	v_ashrrev_i32_e32 v3, 31, v2
	v_mov_b32_e32 v7, v4
	v_lshlrev_b64 v[2:3], 12, v[2:3]
	v_lshl_add_u64 v[2:3], v[166:167], 0, v[2:3]
	v_readfirstlane_b32 s100, v6
	v_readfirstlane_b32 s101, v7
	s_add_u32 m0, s98, 0x0
	s_nop 4
	global_load_lds_dwordx4 v244, s[100:101]
	s_add_u32 m0, s98, 0x400
	s_nop 0
	global_load_lds_dwordx4 v245, s[100:101]
	s_add_u32 m0, s98, 0x800
	s_nop 0
	global_load_lds_dwordx4 v246, s[100:101]
	s_add_u32 m0, s98, 0xc00
	s_nop 0
	global_load_lds_dwordx4 v247, s[100:101]
	v_and_b32_e32 v230, 63, v199
	v_lshlrev_b32_e32 v230, 4, v230
	v_sub_u32_e32 v230, 0, v230
	v_ashrrev_i32_e32 v231, 31, v230
	v_lshl_add_u64 v[230:231], v[2:3], 0, v[230:231]
	global_load_dwordx4 v[110:113], v[230:231], off
	global_load_dwordx4 v[106:109], v[230:231], off offset:1024
	global_load_dwordx4 v[102:105], v[230:231], off offset:2048
	global_load_dwordx4 v[98:101], v[230:231], off offset:3072
	s_waitcnt vmcnt(12)
	ds_read_b128 v[66:69], v234 offset:4096
	ds_read_b128 v[154:157], v235 offset:4096
	ds_read_b128 v[150:153], v236 offset:4096
	ds_read_b128 v[146:149], v237 offset:4096
	s_waitcnt lgkmcnt(3)
	v_mfma_f32_32x32x16_bf16 v[66:81], v[66:69], v[90:93], 0
	v_cndmask_b32_e32 v2, v219, v187, vcc
	v_cmp_gt_u32_e32 vcc, s9, v2
	s_waitcnt lgkmcnt(2)
	v_mfma_f32_32x32x16_bf16 v[66:81], v[154:157], v[82:85], v[66:81]
	s_waitcnt lgkmcnt(1)
	v_mfma_f32_32x32x16_bf16 v[66:81], v[150:153], v[86:89], v[66:81]
	s_waitcnt lgkmcnt(0)
	v_mfma_f32_32x32x16_bf16 v[66:81], v[146:149], v[94:97], v[66:81]
	s_cbranch_vccz .LBB0_861
	v_cmp_le_u32_e32 vcc, v163, v2
	s_nop 9
	v_cndmask_b32_e32 v66, v212, v66, vcc
	v_cmp_le_u32_e32 vcc, v172, v2
	s_nop 1
	v_cndmask_b32_e32 v67, v212, v67, vcc
	v_cmp_le_u32_e32 vcc, v173, v2
	s_nop 1
	v_cndmask_b32_e32 v68, v212, v68, vcc
	v_cmp_le_u32_e32 vcc, v174, v2
	s_nop 1
	v_cndmask_b32_e32 v69, v212, v69, vcc
	v_cmp_le_u32_e32 vcc, v175, v2
	s_nop 1
	v_cndmask_b32_e32 v70, v212, v70, vcc
	v_cmp_le_u32_e32 vcc, v176, v2
	s_nop 1
	v_cndmask_b32_e32 v71, v212, v71, vcc
	v_cmp_le_u32_e32 vcc, v177, v2
	s_nop 1
	v_cndmask_b32_e32 v72, v212, v72, vcc
	v_cmp_le_u32_e32 vcc, v178, v2
	s_nop 1
	v_cndmask_b32_e32 v73, v212, v73, vcc
	v_cmp_le_u32_e32 vcc, v179, v2
	s_nop 1
	v_cndmask_b32_e32 v74, v212, v74, vcc
	v_cmp_le_u32_e32 vcc, v180, v2
	s_nop 1
	v_cndmask_b32_e32 v75, v212, v75, vcc
	v_cmp_le_u32_e32 vcc, v181, v2
	s_nop 1
	v_cndmask_b32_e32 v76, v212, v76, vcc
	v_cmp_le_u32_e32 vcc, v182, v2
	s_nop 1
	v_cndmask_b32_e32 v77, v212, v77, vcc
	v_cmp_le_u32_e32 vcc, v183, v2
	s_nop 1
	v_cndmask_b32_e32 v78, v212, v78, vcc
	v_cmp_le_u32_e32 vcc, v184, v2
	s_nop 1
	v_cndmask_b32_e32 v79, v212, v79, vcc
	v_cmp_le_u32_e32 vcc, v185, v2
	s_nop 1
	v_cndmask_b32_e32 v80, v212, v80, vcc
	v_cmp_le_u32_e32 vcc, v186, v2
	s_nop 1
	v_cndmask_b32_e32 v81, v212, v81, vcc
